# attention: unpacked pk_add row sums, trimmed max tree, invariant LDS addresses hoisted, v_perm V-pack
# speedup vs baseline: 1.0168x; 1.0075x over previous
; __device__ __forceinline__ KP kp_fresh(KP k) { asm volatile("" : "+s"(k)); return k; }
; __device__ __forceinline__ int tid_fresh(int wid) { return wid * 64 + lane_id(); }
; __device__ __forceinline__ void attn_phase(LAS unsigned char* lds, KP kp, int wid0) {
;     kp = kp_fresh(kp); unsigned char* ws = kp->ws;
;     const bf16* Q = (const bf16*)(ws + WS_Q); const bf16* KV = (const bf16*)(ws + WS_KV); const bf16* KR = (const bf16*)(ws + WS_KR); bf16* O = (bf16*)(ws + WS_O);
;     const int tid = tid_fresh(wid0), lane = tid & 63, wid = tid >> 6, r32 = lane & 31, hi = lane >> 5;
;     const int key_l = tid >> 3, c8 = tid & 7;
;     const int kp2 = tid >> 4, g4 = tid & 15;
;     (void)lane;
;     for (int bh = blockIdx.x; bh < NB * NHD; bh += gridDim.x) {
;         const int b = bh >> 4, h = bh & 15, rowb = b * LL;
;         bf16x8 qr[6];
;         u32x4 kregA, rregA = {}, kregB, rregB = {}; u32x2 vaA, vbA, vaB, vbB;
.LBB0_408:
	s_or_b64 exec, exec, s[2:3]
	v_readlane_b32 s0, v255, 3
	v_readlane_b32 s1, v255, 4
	s_mov_b64 s[2:3], s[88:89]
	s_andn2_b64 vcc, exec, s[0:1]
	s_waitcnt lgkmcnt(0)
	s_barrier
	v_mbcnt_lo_u32_b32 v1, -1, 0
	v_mbcnt_hi_u32_b32 v1, -1, v1
	s_cbranch_vccnz .LBB0_477
	s_load_dwordx2 s[0:1], s[2:3], 0x98
	v_add_u32_e32 v2, s61, v1
	v_ashrrev_i32_e32 v11, 6, v2
	v_lshlrev_b32_e32 v12, 5, v11
	v_lshlrev_b32_e32 v4, 4, v1
	v_and_b32_e32 v165, 31, v1
	s_waitcnt lgkmcnt(0)
	s_add_u32 s100, s0, 0xabb0000
	s_addc_u32 s101, s1, 0
	s_add_u32 s48, s0, 0xadb4000
	v_add_u32_e32 v195, 0xffffff10, v12
	v_and_b32_e32 v4, 48, v4
	v_mov_b32_e32 v239, v4
	v_mov_b32_e32 v5, v0
	v_ashrrev_i32_e32 v194, 3, v2
	v_ashrrev_i32_e32 v3, 4, v2
	s_addc_u32 s49, s1, 0
	v_and_b32_e32 v7, 7, v1
	v_add_u32_e32 v2, v195, v165
	v_lshl_add_u64 v[4:5], s[0:1], 0, v[4:5]
	s_mov_b64 s[2:3], 0xabb0000
	s_add_u32 s60, s0, 0x10e74000
	v_max_i32_e32 v196, 0, v2
	v_lshlrev_b32_e32 v2, 3, v7
	v_lshl_add_u64 v[166:167], v[4:5], 0, s[2:3]
	v_lshlrev_b32_e32 v6, 4, v7
	v_mov_b32_e32 v238, v6
	v_cmp_gt_u32_e64 s[2:3], 4, v7
	v_mov_b32_e32 v7, v0
	s_addc_u32 s61, s1, 0
	s_movk_i32 s5, 0xd0
	v_lshl_add_u64 v[8:9], s[0:1], 0, v[6:7]
	s_mov_b64 s[0:1], 0x5300000
	v_lshl_add_u64 v[168:169], v[8:9], 0, s[0:1]
	v_mad_u32_u24 v198, v165, s5, 0
	s_movk_i32 s1, 0xffb8
	v_mad_i32_i24 v200, v165, s1, v198
	s_movk_i32 s0, 0x48
	v_lshl_add_u64 v[170:171], s[60:61], 0, v[6:7]
	v_mad_u32_u24 v202, v165, s0, v200
	v_or_b32_e32 v7, v165, v12
	s_movk_i32 s0, 0x1200
	v_lshlrev_b32_e32 v4, 2, v1
	v_add_u32_e32 v204, 16, v7
	v_mul_lo_u32 v7, v11, s0
	v_bfe_u32 v10, v1, 5, 1
	v_and_b32_e32 v4, 60, v4
	v_mul_lo_u32 v5, v194, s5
	s_movk_i32 s4, 0x88
	v_add_u32_e32 v7, 0, v7
	s_movk_i32 s0, 0x90
	v_bfe_u32 v205, v1, 3, 3
	v_lshlrev_b32_e32 v164, 3, v10
	v_lshlrev_b32_e32 v197, 1, v3
	v_add_u32_e32 v5, 0, v5
	v_mad_u32_u24 v13, v4, s4, 0
	v_lshlrev_b32_e32 v3, 2, v3
	v_mad_u32_u24 v8, v165, s0, v7
	v_add_u32_e32 v1, v7, v6
	v_mul_u32_u24_e32 v7, 0x90, v205
	v_lshlrev_b32_e32 v199, 4, v10
	v_lshlrev_b32_e32 v201, 2, v10
	v_mad_i32_i24 v203, v165, s1, v202
	v_or_b32_e32 v206, 8, v205
	v_or_b32_e32 v207, 16, v205
	v_or_b32_e32 v208, 24, v205
	v_lshlrev_b32_e32 v172, 1, v2
	v_lshlrev_b32_e32 v174, 1, v4
	v_add_u32_e32 v209, v8, v164
	v_add_u32_e32 v210, v5, v6
	v_add_u32_e32 v211, v13, v3
	v_add_u32_e32 v212, v1, v7
	v_add_u32_e32 v240, v198, v199
	v_add_u32_e32 v241, v202, v199
	v_add_u32_e32 v250, v200, v164
	v_add_u32_e32 v251, 0x9800, v250
	v_add_u32_e32 v250, 0x8800, v250
	v_add_u32_e32 v252, v203, v164
	v_add_u32_e32 v253, 0x7800, v252
	v_add_u32_e32 v252, 0x6800, v252
	v_add_u32_e32 v254, 0x8800, v211
	s_mov_b32 s94, 0x5040100
	s_mov_b32 s95, 0x7060302
	s_mov_b32 s0, s33
	s_branch .LBB0_411

.LBB0_416:
	s_or_b64 exec, exec, s[4:5]
	s_waitcnt vmcnt(4)
	v_perm_b32 v10, v192, v14, s94
	v_perm_b32 v11, v192, v14, s95
	ds_write2_b32 v254, v10, v11 offset0:128 offset1:162
	v_perm_b32 v10, v193, v15, s94
	v_perm_b32 v11, v193, v15, s95
	ds_write2_b32 v254, v10, v11 offset0:196 offset1:230
	s_waitcnt lgkmcnt(0)
	s_barrier

; #define LAS __attribute__((address_space(3)))
; __device__ __forceinline__ void qk_tile(f32x16& s0, f32x16& s1, LAS unsigned char* kb, const bf16x8 (&qr)[6], const f32x16& negm, int r32, int hi) {
;     bf16x8 kf[12];
; #pragma unroll
;     for (int ks = 0; ks < 6; ++ks) { kf[2 * ks] = *(const LAS bf16x8*)(kb + r32 * KPT + ks * 32 + hi * 16); kf[2 * ks + 1] = *(const LAS bf16x8*)(kb + (32 + r32) * KPT + ks * 32 + hi * 16); }
;     __builtin_amdgcn_sched_barrier(0);
; #pragma unroll
;     for (int ks = 0; ks < 6; ++ks) {
;         s0 = __builtin_amdgcn_mfma_f32_32x32x16_bf16(kf[2 * ks], qr[ks], ks == 0 ? negm : s0, 0, 0, 0);
;         s1 = __builtin_amdgcn_mfma_f32_32x32x16_bf16(kf[2 * ks + 1], qr[ks], ks == 0 ? negm : s1, 0, 0, 0);
;     }
; }
; __device__ __forceinline__ void sm_pv(f32x16& s0, f32x16& s1, f32x16& o0, f32x16& o1, float& m_run, float& l_run, f32x16& negm, LAS unsigned char* vb, bool domask, int kbase, int qm, int r32, int hi) {
;     s16x4 vlo[8], vhh[8];
; #pragma unroll
;     for (int kk = 0; kk < 4; ++kk) { const int koff = 2 * (16 * kk + 4 * hi);
;         vlo[2 * kk] = *(const LAS s16x4*)(vb + r32 * VP + koff); vhh[2 * kk] = *(const LAS s16x4*)(vb + r32 * VP + koff + 16);
;         vlo[2 * kk + 1] = *(const LAS s16x4*)(vb + (32 + r32) * VP + koff); vhh[2 * kk + 1] = *(const LAS s16x4*)(vb + (32 + r32) * VP + koff + 16); }
;     __builtin_amdgcn_sched_barrier(0);
;     if (domask) {
;         const int kb0 = kbase + 4 * hi;
; #pragma unroll
;         for (int r = 0; r < 16; ++r) { const int kv = kb0 + (r & 3) + 8 * (r >> 2); if (kv > qm) s0[r] = -INFINITY; if (kv + 32 > qm) s1[r] = -INFINITY; }
.LBB0_418:
	s_add_i32 s85, s84, -3
	s_cmp_lt_u32 s85, s57
	s_cselect_b64 s[44:45], -1, 0
	s_and_b64 s[4:5], s[44:45], exec
	s_cselect_b32 s4, 0, s79
	s_lshl_b32 s4, s4, 6
	v_add_u32_e32 v221, s83, v213
	v_add_u32_e32 v222, s83, v173
	s_sub_i32 s5, 0x80, s4
	s_waitcnt vmcnt(3)
	v_add_u32_e32 v2, s5, v221
	v_add_u32_e32 v10, s5, v222
	v_min_u32_e32 v2, 0x80ff, v2
	v_add_u32_e32 v12, 1, v10
	v_min_u32_e32 v10, 0x80ff, v10
	v_min_u32_e32 v12, 0x80ff, v12
	v_lshl_add_u32 v4, v2, 12, v238
	s_waitcnt vmcnt(2)
	v_lshl_add_u32 v6, v2, 6, v239
	v_lshl_add_u32 v10, v10, 12, v174
	v_lshl_add_u32 v12, v12, 12, v174
	global_load_dwordx4 v[2:5], v4, s[98:99]
	s_nop 0
	global_load_dwordx4 v[6:9], v6, s[100:101]
	global_load_dwordx2 v[14:15], v10, s[98:99] offset:128
	global_load_dwordx2 v[192:193], v12, s[98:99] offset:128
	v_cmp_le_u32_e32 vcc, s83, v220
	s_and_saveexec_b64 s[46:47], vcc
	s_cbranch_execz .LBB0_426
	ds_read_b128 v[10:13], v240 offset:13312
	ds_read_b128 v[136:139], v240 offset:13344
	ds_read_b128 v[140:143], v240 offset:19968
	ds_read_b128 v[144:147], v240 offset:20000
	ds_read_b128 v[148:151], v240 offset:13376
	ds_read_b128 v[152:155], v240 offset:13408
	ds_read_b128 v[156:159], v240 offset:20032
	ds_read_b128 v[160:163], v240 offset:20064
	ds_read_b128 v[224:227], v240 offset:13440
	ds_read_b128 v[228:231], v240 offset:13472
	ds_read_b128 v[232:235], v240 offset:20096
	ds_read_b128 v[246:249], v240 offset:20128
	s_waitcnt lgkmcnt(11)
	v_mfma_f32_32x32x16_bf16 v[80:95], v[10:13], v[96:99], v[48:63]
	s_add_i32 s4, s83, 63
	v_cmp_gt_i32_e32 vcc, s4, v175
	s_waitcnt lgkmcnt(9)
	v_mfma_f32_32x32x16_bf16 v[64:79], v[140:143], v[96:99], v[48:63]
	v_mfma_f32_32x32x16_bf16 v[80:95], v[136:139], v[100:103], v[80:95]
	s_waitcnt lgkmcnt(8)
	v_mfma_f32_32x32x16_bf16 v[64:79], v[144:147], v[100:103], v[64:79]
	s_waitcnt lgkmcnt(7)
	v_mfma_f32_32x32x16_bf16 v[80:95], v[148:151], v[104:107], v[80:95]
	s_waitcnt lgkmcnt(5)
	v_mfma_f32_32x32x16_bf16 v[64:79], v[156:159], v[104:107], v[64:79]
	v_mfma_f32_32x32x16_bf16 v[80:95], v[152:155], v[108:111], v[80:95]
	ds_read2_b64 v[152:155], v250 offset0:68 offset1:70
	s_waitcnt lgkmcnt(5)
	v_mfma_f32_32x32x16_bf16 v[64:79], v[160:163], v[108:111], v[64:79]
	ds_read2_b64 v[160:163], v250 offset0:64 offset1:66
	ds_read2_b64 v[156:159], v251 offset0:96 offset1:98
	ds_read2_b64 v[148:151], v251 offset0:100 offset1:102
	ds_read2_b64 v[144:147], v250 offset0:72 offset1:74
	ds_read2_b64 v[140:143], v251 offset0:104 offset1:106
	ds_read2_b64 v[136:139], v250 offset0:76 offset1:78
	ds_read2_b64 v[10:13], v251 offset0:108 offset1:110
	s_waitcnt lgkmcnt(11)
	v_mfma_f32_32x32x16_bf16 v[80:95], v[224:227], v[112:115], v[80:95]
	s_waitcnt lgkmcnt(9)
	v_mfma_f32_32x32x16_bf16 v[64:79], v[232:235], v[112:115], v[64:79]
	v_mfma_f32_32x32x16_bf16 v[80:95], v[228:231], v[116:119], v[80:95]
	s_waitcnt lgkmcnt(8)
	v_mfma_f32_32x32x16_bf16 v[64:79], v[246:249], v[116:119], v[64:79]
	s_and_saveexec_b64 s[58:59], vcc
	s_cbranch_execz .LBB0_423
	v_add_u32_e32 v223, s83, v201
	v_add_u32_e32 v224, 32, v223
	v_cmp_ge_i32_e64 s[4:5], v177, v224
	v_add_u32_e32 v224, 33, v223
	v_cmp_ge_i32_e64 s[6:7], v177, v224
	v_add_u32_e32 v224, 2, v223
	v_cmp_le_u32_e32 vcc, v223, v219
	s_nop 2
	v_cndmask_b32_e64 v65, v244, v65, s[6:7]
	v_cmp_ge_i32_e64 s[6:7], v177, v224
	v_add_u32_e32 v224, 34, v223
	v_cmp_ge_i32_e64 s[8:9], v177, v224
	v_add_u32_e32 v224, 3, v223
	v_cndmask_b32_e64 v64, v244, v64, s[4:5]
	v_cndmask_b32_e64 v66, v244, v66, s[8:9]
	v_cmp_ge_i32_e64 s[8:9], v177, v224
	v_add_u32_e32 v224, 35, v223
	v_cmp_ge_i32_e64 s[10:11], v177, v224
	v_add_u32_e32 v224, 8, v223
	v_cmp_gt_i32_e64 s[4:5], v177, v223
	v_cndmask_b32_e64 v67, v244, v67, s[10:11]
	v_cmp_ge_i32_e64 s[10:11], v177, v224
	v_add_u32_e32 v224, 40, v223
	v_cmp_ge_i32_e64 s[12:13], v177, v224
	v_add_u32_e32 v224, 9, v223
	s_nop 0
	v_cndmask_b32_e64 v68, v244, v68, s[12:13]
	v_cmp_ge_i32_e64 s[12:13], v177, v224
	v_add_u32_e32 v224, 41, v223
	v_cmp_ge_i32_e64 s[14:15], v177, v224
	v_add_u32_e32 v224, 10, v223
	s_nop 0
	v_cndmask_b32_e64 v69, v244, v69, s[14:15]
	v_cmp_ge_i32_e64 s[14:15], v177, v224
	v_add_u32_e32 v224, 42, v223
	v_cmp_ge_i32_e64 s[16:17], v177, v224
	v_add_u32_e32 v224, 11, v223
	s_nop 0
	v_cndmask_b32_e64 v70, v244, v70, s[16:17]
	v_cmp_ge_i32_e64 s[16:17], v177, v224
	v_add_u32_e32 v224, 43, v223
	v_cmp_ge_i32_e64 s[18:19], v177, v224
	v_add_u32_e32 v224, 16, v223
	s_nop 0
	v_cndmask_b32_e64 v71, v244, v71, s[18:19]
	v_cmp_ge_i32_e64 s[18:19], v177, v224
	v_add_u32_e32 v224, 48, v223
	v_cmp_ge_i32_e64 s[20:21], v177, v224
	v_add_u32_e32 v224, 17, v223
	s_nop 0
	v_cndmask_b32_e64 v72, v244, v72, s[20:21]
	v_cmp_ge_i32_e64 s[20:21], v177, v224
	v_add_u32_e32 v224, 49, v223
	v_cmp_ge_i32_e64 s[22:23], v177, v224
	v_add_u32_e32 v224, 18, v223
	s_nop 0
	v_cndmask_b32_e64 v73, v244, v73, s[22:23]
	v_cmp_ge_i32_e64 s[22:23], v177, v224
	v_add_u32_e32 v224, 50, v223
	v_cmp_ge_i32_e64 s[24:25], v177, v224
	v_add_u32_e32 v224, 19, v223
	s_nop 0
	v_cndmask_b32_e64 v74, v244, v74, s[24:25]
	v_cmp_ge_i32_e64 s[24:25], v177, v224
	v_add_u32_e32 v224, 51, v223
	v_cmp_ge_i32_e64 s[26:27], v177, v224
	v_add_u32_e32 v224, 24, v223
	s_nop 0
	v_cndmask_b32_e64 v75, v244, v75, s[26:27]
	v_cmp_ge_i32_e64 s[26:27], v177, v224
	v_add_u32_e32 v224, 56, v223
	v_cmp_ge_i32_e64 s[28:29], v177, v224
	v_add_u32_e32 v224, 25, v223
	s_nop 0
	v_cndmask_b32_e64 v76, v244, v76, s[28:29]
	v_cmp_ge_i32_e64 s[28:29], v177, v224
	v_add_u32_e32 v224, 57, v223
	v_cmp_ge_i32_e64 s[30:31], v177, v224
	v_add_u32_e32 v224, 26, v223
	s_nop 0
	v_cndmask_b32_e64 v77, v244, v77, s[30:31]
	v_cmp_ge_i32_e64 s[30:31], v177, v224
	v_add_u32_e32 v224, 58, v223
	v_cmp_ge_i32_e64 s[34:35], v177, v224
	v_add_u32_e32 v224, 27, v223
	v_add_u32_e32 v223, 59, v223
	v_cndmask_b32_e64 v78, v244, v78, s[34:35]
	v_cmp_ge_i32_e64 s[34:35], v177, v224
	v_cmp_lt_i32_e64 s[36:37], v177, v223
	s_and_saveexec_b64 s[40:41], s[36:37]
	v_mov_b32_e32 v79, s52
	s_or_b64 exec, exec, s[40:41]
	v_cndmask_b32_e32 v80, v244, v80, vcc
	v_cndmask_b32_e64 v81, v244, v81, s[4:5]
	v_cndmask_b32_e64 v82, v244, v82, s[6:7]
	v_cndmask_b32_e64 v83, v244, v83, s[8:9]
	v_cndmask_b32_e64 v84, v244, v84, s[10:11]
	v_cndmask_b32_e64 v85, v244, v85, s[12:13]
	v_cndmask_b32_e64 v86, v244, v86, s[14:15]
	v_cndmask_b32_e64 v87, v244, v87, s[16:17]
	v_cndmask_b32_e64 v88, v244, v88, s[18:19]
	v_cndmask_b32_e64 v89, v244, v89, s[20:21]
	v_cndmask_b32_e64 v90, v244, v90, s[22:23]
	v_cndmask_b32_e64 v91, v244, v91, s[24:25]
	v_cndmask_b32_e64 v92, v244, v92, s[26:27]
	v_cndmask_b32_e64 v93, v244, v93, s[28:29]
	v_cndmask_b32_e64 v94, v244, v94, s[30:31]
	v_cndmask_b32_e64 v95, v244, v95, s[34:35]
; __device__ __forceinline__ unsigned cvtpk(float lo, float hi) { const f32x2 v = {lo, hi}; const bf16x2_t b = __builtin_convertvector(v, bf16x2_t); return __builtin_bit_cast(unsigned, b); }
; __device__ __forceinline__ void sm_pv(f32x16& s0, f32x16& s1, f32x16& o0, f32x16& o1, float& m_run, float& l_run, f32x16& negm, LAS unsigned char* vb, bool domask, int kbase, int qm, int r32, int hi) {
;     ...
;     float ma = fmaxf(fmaxf(s0[0], s0[1]), s1[0]), mb = fmaxf(fmaxf(s0[2], s0[3]), s1[1]);
;     ma = fmaxf(fmaxf(ma, s1[2]), s1[3]);
; #pragma unroll
;     for (int r = 4; r < 16; r += 4) { ma = fmaxf(fmaxf(ma, s0[r]), s0[r + 1]); mb = fmaxf(fmaxf(mb, s0[r + 2]), s0[r + 3]); ma = fmaxf(fmaxf(ma, s1[r]), s1[r + 1]); mb = fmaxf(fmaxf(mb, s1[r + 2]), s1[r + 3]); }
;     float mx = fmaxf(ma, mb);
;     { const auto rr = __builtin_amdgcn_permlane32_swap(__float_as_uint(mx), __float_as_uint(mx), false, false); mx = fmaxf(__uint_as_float(rr[0]), __uint_as_float(rr[1])); }
;     if (__builtin_amdgcn_ballot_w64(mx > 8.0f) != 0ull) {
;         const float d = fmaxf(mx, 0.0f);
;         const float alpha = __builtin_amdgcn_exp2f(-d);
;         m_run += d; l_run *= alpha; o0 = o0 * alpha; o1 = o1 * alpha;
;         s0 = s0 - d; s1 = s1 - d;
; #pragma unroll
;         for (int r = 0; r < 16; ++r) negm[r] = -m_run;
;     }
;     f32x2 ps2 = (f32x2){0.f, 0.f};
; #pragma unroll
;     for (int r = 0; r < 16; r += 2) { s0[r] = __builtin_amdgcn_exp2f(s0[r]); s0[r + 1] = __builtin_amdgcn_exp2f(s0[r + 1]); s1[r] = __builtin_amdgcn_exp2f(s1[r]); s1[r + 1] = __builtin_amdgcn_exp2f(s1[r + 1]);
;         ps2 += (f32x2){s0[r], s0[r + 1]}; ps2 += (f32x2){s1[r], s1[r + 1]}; }
;     l_run += ps2[0] + ps2[1];
;     u32x4 pw[4];
; #pragma unroll
;     for (int i = 0; i < 4; ++i) { pw[0][i] = cvtpk(s0[2 * i], s0[2 * i + 1]); pw[1][i] = cvtpk(s0[8 + 2 * i], s0[8 + 2 * i + 1]); pw[2][i] = cvtpk(s1[2 * i], s1[2 * i + 1]); pw[3][i] = cvtpk(s1[8 + 2 * i], s1[8 + 2 * i + 1]); }
.LBB0_423:
	s_or_b64 exec, exec, s[58:59]
	s_nop 6
	v_max_f32_e32 v223, v80, v81
	v_max3_f32 v224, v82, v83, v65
	v_max3_f32 v223, v223, v64, v66
	v_max3_f32 v223, v223, v67, v84
	v_max3_f32 v224, v224, v86, v87
	v_max3_f32 v223, v223, v85, v68
	v_max3_f32 v224, v224, v70, v71
	v_max3_f32 v223, v223, v69, v88
	v_max3_f32 v224, v224, v90, v91
	v_max3_f32 v223, v223, v89, v72
	v_max3_f32 v224, v224, v74, v75
	v_max3_f32 v223, v223, v73, v92
	v_max3_f32 v224, v224, v94, v95
	v_max3_f32 v223, v223, v93, v76
	v_max3_f32 v224, v224, v78, v79
	v_max3_f32 v223, v223, v77, v224
	v_mov_b32_e32 v224, v223
	s_nop 1
	v_permlane32_swap_b32_e32 v223, v224
	v_max_f32_e32 v223, v223, v224
	v_cmp_lt_f32_e32 vcc, s53, v223
	s_cbranch_vccz .LBB0_425
	v_max_f32_e32 v48, v223, v223
	v_max_f32_e32 v49, 0, v48
	v_exp_f32_e64 v48, -v49
	v_add_f32_e32 v1, v1, v49
	v_sub_f32_e32 v80, v80, v49
	v_sub_f32_e32 v81, v81, v49
	v_mul_f32_e32 v218, v218, v48
	v_pk_mul_f32 v[46:47], v[46:47], v[48:49] op_sel_hi:[1,0]
	v_pk_mul_f32 v[44:45], v[44:45], v[48:49] op_sel_hi:[1,0]
	v_pk_mul_f32 v[42:43], v[42:43], v[48:49] op_sel_hi:[1,0]
	v_pk_mul_f32 v[40:41], v[40:41], v[48:49] op_sel_hi:[1,0]
	v_pk_mul_f32 v[38:39], v[38:39], v[48:49] op_sel_hi:[1,0]
	v_pk_mul_f32 v[36:37], v[36:37], v[48:49] op_sel_hi:[1,0]
	v_pk_mul_f32 v[34:35], v[34:35], v[48:49] op_sel_hi:[1,0]
	v_pk_mul_f32 v[32:33], v[32:33], v[48:49] op_sel_hi:[1,0]
	v_pk_mul_f32 v[30:31], v[30:31], v[48:49] op_sel_hi:[1,0]
	v_pk_mul_f32 v[28:29], v[28:29], v[48:49] op_sel_hi:[1,0]
	v_pk_mul_f32 v[26:27], v[26:27], v[48:49] op_sel_hi:[1,0]
	v_pk_mul_f32 v[24:25], v[24:25], v[48:49] op_sel_hi:[1,0]
	v_pk_mul_f32 v[22:23], v[22:23], v[48:49] op_sel_hi:[1,0]
	v_pk_mul_f32 v[20:21], v[20:21], v[48:49] op_sel_hi:[1,0]
	v_pk_mul_f32 v[18:19], v[18:19], v[48:49] op_sel_hi:[1,0]
	v_pk_mul_f32 v[16:17], v[16:17], v[48:49] op_sel_hi:[1,0]
	v_xor_b32_e32 v48, 0x80000000, v1
	v_sub_f32_e32 v82, v82, v49
	v_sub_f32_e32 v83, v83, v49
	v_sub_f32_e32 v84, v84, v49
	v_sub_f32_e32 v85, v85, v49
	v_sub_f32_e32 v86, v86, v49
	v_sub_f32_e32 v87, v87, v49
	v_sub_f32_e32 v88, v88, v49
	v_sub_f32_e32 v89, v89, v49
	v_sub_f32_e32 v90, v90, v49
	v_sub_f32_e32 v91, v91, v49
	v_sub_f32_e32 v92, v92, v49
	v_sub_f32_e32 v93, v93, v49
	v_sub_f32_e32 v94, v94, v49
	v_sub_f32_e32 v95, v95, v49
	v_sub_f32_e32 v64, v64, v49
	v_sub_f32_e32 v65, v65, v49
	v_sub_f32_e32 v66, v66, v49
	v_sub_f32_e32 v67, v67, v49
	v_sub_f32_e32 v68, v68, v49
	v_sub_f32_e32 v69, v69, v49
	v_sub_f32_e32 v70, v70, v49
	v_sub_f32_e32 v71, v71, v49
	v_sub_f32_e32 v72, v72, v49
	v_sub_f32_e32 v73, v73, v49
	v_sub_f32_e32 v74, v74, v49
	v_sub_f32_e32 v75, v75, v49
	v_sub_f32_e32 v76, v76, v49
	v_sub_f32_e32 v77, v77, v49
	v_sub_f32_e32 v78, v78, v49
	v_sub_f32_e32 v79, v79, v49
	v_mov_b32_e32 v49, v48
	v_mov_b32_e32 v50, v48
	v_mov_b32_e32 v51, v48
	v_mov_b32_e32 v52, v48
	v_mov_b32_e32 v53, v48
	v_mov_b32_e32 v54, v48
	v_mov_b32_e32 v55, v48
	v_mov_b32_e32 v56, v48
	v_mov_b32_e32 v57, v48
	v_mov_b32_e32 v58, v48
	v_mov_b32_e32 v59, v48
	v_mov_b32_e32 v60, v48
	v_mov_b32_e32 v61, v48
	v_mov_b32_e32 v62, v48
	v_mov_b32_e32 v63, v48
.LBB0_425:
	v_exp_f32_e32 v80, v80
	v_exp_f32_e32 v81, v81
	v_exp_f32_e32 v228, v82
	v_exp_f32_e32 v229, v83
	v_exp_f32_e32 v84, v84
	v_exp_f32_e32 v85, v85
	v_exp_f32_e32 v86, v86
	v_exp_f32_e32 v87, v87
	v_exp_f32_e32 v224, v64
	v_exp_f32_e32 v225, v65
	v_add_f32_e32 v64, 0, v80
	v_add_f32_e32 v65, 0, v81
	v_cvt_pk_bf16_f32 v80, v80, v81
	v_cvt_pk_bf16_f32 v81, v228, v229
	v_cvt_pk_bf16_f32 v82, v84, v85
	v_cvt_pk_bf16_f32 v83, v86, v87
	v_exp_f32_e32 v88, v88
	v_exp_f32_e32 v89, v89
	s_waitcnt lgkmcnt(6)
	v_mfma_f32_32x32x16_bf16 v[32:47], v[160:163], v[80:83], v[32:47]
	v_exp_f32_e32 v90, v90
	v_exp_f32_e32 v91, v91
	v_exp_f32_e32 v92, v92
	v_exp_f32_e32 v93, v93
	v_add_f32_e32 v226, v224, v64
	v_add_f32_e32 v227, v225, v65
	v_exp_f32_e32 v230, v66
	v_exp_f32_e32 v231, v67
	s_waitcnt lgkmcnt(5)
	v_mfma_f32_32x32x16_bf16 v[16:31], v[156:159], v[80:83], v[16:31]
	v_exp_f32_e32 v80, v94
	v_exp_f32_e32 v81, v95
	v_cvt_pk_bf16_f32 v64, v88, v89
	v_cvt_pk_bf16_f32 v65, v90, v91
	v_cvt_pk_bf16_f32 v66, v92, v93
	v_cvt_pk_bf16_f32 v67, v80, v81
	v_exp_f32_e32 v68, v68
	v_exp_f32_e32 v69, v69
	v_mfma_f32_32x32x16_bf16 v[32:47], v[152:155], v[64:67], v[32:47]
	v_exp_f32_e32 v70, v70
	v_exp_f32_e32 v71, v71
	v_add_f32_e32 v82, v228, v226
	v_add_f32_e32 v83, v229, v227
	v_exp_f32_e32 v72, v72
	v_add_f32_e32 v82, v230, v82
	v_add_f32_e32 v83, v231, v83
	v_exp_f32_e32 v73, v73
	v_add_f32_e32 v82, v84, v82
	v_add_f32_e32 v83, v85, v83
	s_waitcnt lgkmcnt(4)
	v_mfma_f32_32x32x16_bf16 v[16:31], v[148:151], v[64:67], v[16:31]
	v_cvt_pk_bf16_f32 v64, v224, v225
	v_cvt_pk_bf16_f32 v65, v230, v231
	v_cvt_pk_bf16_f32 v66, v68, v69
	v_cvt_pk_bf16_f32 v67, v70, v71
	v_add_f32_e64 v82, v68, v82
	v_add_f32_e64 v83, v69, v83
	v_add_f32_e32 v82, v86, v82
	v_add_f32_e32 v83, v87, v83
	s_waitcnt lgkmcnt(3)
	v_mfma_f32_32x32x16_bf16 v[32:47], v[144:147], v[64:67], v[32:47]
	v_add_f32_e64 v68, v70, v82
	v_add_f32_e64 v69, v71, v83
	v_exp_f32_e32 v70, v74
	v_exp_f32_e32 v71, v75
	v_exp_f32_e32 v74, v76
	v_exp_f32_e32 v75, v77
	v_exp_f32_e32 v76, v78
	v_exp_f32_e32 v77, v79
	s_waitcnt lgkmcnt(2)
	v_mfma_f32_32x32x16_bf16 v[16:31], v[140:143], v[64:67], v[16:31]
	v_add_f32_e64 v68, v88, v68
	v_add_f32_e64 v69, v89, v69
	v_cvt_pk_bf16_f32 v64, v72, v73
	v_add_f32_e64 v68, v72, v68
	v_add_f32_e64 v69, v73, v69
	v_cvt_pk_bf16_f32 v65, v70, v71
	v_cvt_pk_bf16_f32 v66, v74, v75
	v_cvt_pk_bf16_f32 v67, v76, v77
	v_add_f32_e32 v68, v90, v68
	v_add_f32_e32 v69, v91, v69
	s_waitcnt lgkmcnt(1)
	v_mfma_f32_32x32x16_bf16 v[32:47], v[136:139], v[64:67], v[32:47]
	v_add_f32_e64 v68, v70, v68
	v_add_f32_e64 v69, v71, v69
	v_add_f32_e64 v68, v92, v68
	v_add_f32_e64 v69, v93, v69
	v_add_f32_e64 v68, v74, v68
	v_add_f32_e64 v69, v75, v69
	v_add_f32_e32 v68, v80, v68
	v_add_f32_e32 v69, v81, v69
	s_waitcnt lgkmcnt(0)
	v_mfma_f32_32x32x16_bf16 v[16:31], v[10:13], v[64:67], v[16:31]
	v_add_f32_e64 v68, v76, v68
	v_add_f32_e64 v69, v77, v69
	v_add_f32_e32 v68, v68, v69
	v_add_f32_e32 v218, v218, v68
; #define LAS __attribute__((address_space(3)))
; __device__ __forceinline__ void qk_tile(f32x16& s0, f32x16& s1, LAS unsigned char* kb, const bf16x8 (&qr)[6], const f32x16& negm, int r32, int hi) {
;     bf16x8 kf[12];
; #pragma unroll
;     for (int ks = 0; ks < 6; ++ks) { kf[2 * ks] = *(const LAS bf16x8*)(kb + r32 * KPT + ks * 32 + hi * 16); kf[2 * ks + 1] = *(const LAS bf16x8*)(kb + (32 + r32) * KPT + ks * 32 + hi * 16); }
;     __builtin_amdgcn_sched_barrier(0);
; #pragma unroll
;     for (int ks = 0; ks < 6; ++ks) {
;         s0 = __builtin_amdgcn_mfma_f32_32x32x16_bf16(kf[2 * ks], qr[ks], ks == 0 ? negm : s0, 0, 0, 0);
;         s1 = __builtin_amdgcn_mfma_f32_32x32x16_bf16(kf[2 * ks + 1], qr[ks], ks == 0 ? negm : s1, 0, 0, 0);
;     }
; }
; __device__ __forceinline__ void sm_pv(f32x16& s0, f32x16& s1, f32x16& o0, f32x16& o1, float& m_run, float& l_run, f32x16& negm, LAS unsigned char* vb, bool domask, int kbase, int qm, int r32, int hi) {
;     s16x4 vlo[8], vhh[8];
; #pragma unroll
;     for (int kk = 0; kk < 4; ++kk) { const int koff = 2 * (16 * kk + 4 * hi);
;         vlo[2 * kk] = *(const LAS s16x4*)(vb + r32 * VP + koff); vhh[2 * kk] = *(const LAS s16x4*)(vb + r32 * VP + koff + 16);
;         vlo[2 * kk + 1] = *(const LAS s16x4*)(vb + (32 + r32) * VP + koff); vhh[2 * kk + 1] = *(const LAS s16x4*)(vb + (32 + r32) * VP + koff + 16); }
.LBB0_426:
	s_or_b64 exec, exec, s[46:47]
	ds_write_b128 v210, v[120:123]
	s_and_saveexec_b64 s[4:5], s[2:3]
	ds_write_b128 v210, v[124:127] offset:128
	s_or_b64 exec, exec, s[4:5]
	s_waitcnt vmcnt(4)
	v_perm_b32 v10, v186, v184, s94
	v_perm_b32 v11, v186, v184, s95
	ds_write2_b32 v214, v10, v11 offset1:34
	v_perm_b32 v10, v187, v185, s94
	v_perm_b32 v11, v187, v185, s95
	ds_write2_b32 v214, v10, v11 offset0:68 offset1:102
	s_waitcnt lgkmcnt(0)
	s_barrier
	s_andn2_b64 vcc, exec, s[44:45]
	s_cbranch_vccnz .LBB0_417
	s_cmp_gt_u32 s84, s57
	s_cselect_b32 s4, s79, 0
	s_lshl_b32 s4, s4, 6
	s_sub_i32 s4, 0xc0, s4
	v_add_u32_e32 v10, s4, v221
	v_add_u32_e32 v11, s4, v222
	v_min_u32_e32 v10, 0x80ff, v10
	v_add_u32_e32 v13, 1, v11
	v_min_u32_e32 v11, 0x80ff, v11
	v_min_u32_e32 v13, 0x80ff, v13
	v_lshl_add_u32 v12, v10, 12, v238
	v_lshl_add_u32 v10, v10, 6, v239
	v_lshl_add_u32 v11, v11, 12, v174
	v_lshl_add_u32 v13, v13, 12, v174
	global_load_dwordx4 v[120:123], v12, s[98:99]
	global_load_dwordx4 v[124:127], v10, s[100:101]
	global_load_dwordx2 v[184:185], v11, s[98:99] offset:128
	global_load_dwordx2 v[186:187], v13, s[98:99] offset:128
	s_add_i32 s4, s83, 64
	v_cmp_le_u32_e32 vcc, s4, v220
	s_and_saveexec_b64 s[44:45], vcc
	s_cbranch_execz .LBB0_437
	ds_read_b128 v[10:13], v241
	ds_read_b128 v[136:139], v241 offset:32
	ds_read_b128 v[140:143], v241 offset:6656
	ds_read_b128 v[144:147], v241 offset:6688
	ds_read_b128 v[148:151], v241 offset:64
	ds_read_b128 v[152:155], v241 offset:96
	ds_read_b128 v[156:159], v241 offset:6720
	ds_read_b128 v[160:163], v241 offset:6752
	ds_read_b128 v[222:225], v241 offset:128
	ds_read_b128 v[226:229], v241 offset:160
	ds_read_b128 v[230:233], v241 offset:6784
	ds_read_b128 v[234:237], v241 offset:6816
	s_waitcnt lgkmcnt(11)
	v_mfma_f32_32x32x16_bf16 v[80:95], v[10:13], v[96:99], v[48:63]
	s_add_i32 s4, s83, 0x7f
	v_cmp_gt_i32_e32 vcc, s4, v175
	s_waitcnt lgkmcnt(9)
	v_mfma_f32_32x32x16_bf16 v[64:79], v[140:143], v[96:99], v[48:63]
	v_mfma_f32_32x32x16_bf16 v[80:95], v[136:139], v[100:103], v[80:95]
	s_waitcnt lgkmcnt(8)
	v_mfma_f32_32x32x16_bf16 v[64:79], v[144:147], v[100:103], v[64:79]
	s_waitcnt lgkmcnt(7)
	v_mfma_f32_32x32x16_bf16 v[80:95], v[148:151], v[104:107], v[80:95]
	s_waitcnt lgkmcnt(5)
	v_mfma_f32_32x32x16_bf16 v[64:79], v[156:159], v[104:107], v[64:79]
	v_mfma_f32_32x32x16_bf16 v[80:95], v[152:155], v[108:111], v[80:95]
	ds_read2_b64 v[152:155], v252 offset0:4 offset1:6
	s_waitcnt lgkmcnt(5)
	v_mfma_f32_32x32x16_bf16 v[64:79], v[160:163], v[108:111], v[64:79]
	ds_read2_b64 v[160:163], v252 offset1:2
	ds_read2_b64 v[156:159], v253 offset0:32 offset1:34
	ds_read2_b64 v[148:151], v253 offset0:36 offset1:38
	ds_read2_b64 v[144:147], v252 offset0:8 offset1:10
	ds_read2_b64 v[140:143], v253 offset0:40 offset1:42
	ds_read2_b64 v[136:139], v252 offset0:12 offset1:14
	ds_read2_b64 v[10:13], v253 offset0:44 offset1:46
	s_waitcnt lgkmcnt(11)
	v_mfma_f32_32x32x16_bf16 v[80:95], v[222:225], v[112:115], v[80:95]
	s_waitcnt lgkmcnt(9)
	v_mfma_f32_32x32x16_bf16 v[64:79], v[230:233], v[112:115], v[64:79]
	v_mfma_f32_32x32x16_bf16 v[80:95], v[226:229], v[116:119], v[80:95]
	s_waitcnt lgkmcnt(8)
	v_mfma_f32_32x32x16_bf16 v[64:79], v[234:237], v[116:119], v[64:79]
	s_and_saveexec_b64 s[46:47], vcc
	s_cbranch_execz .LBB0_434
	v_add_u32_e32 v221, s83, v201
	v_add_u32_e32 v223, 0x60, v221
	v_add_u32_e32 v222, 64, v221
	v_cmp_le_u32_e64 s[4:5], v223, v219
	v_cmp_le_u32_e32 vcc, v222, v219
	s_nop 4
	v_cndmask_b32_e64 v64, v244, v64, s[4:5]
	v_cmp_lt_u32_e64 s[4:5], v222, v219
	v_add_u32_e32 v222, 0x61, v221
	v_cmp_le_u32_e64 s[6:7], v222, v219
	v_add_u32_e32 v222, 0x42, v221
	s_nop 0
	v_cndmask_b32_e64 v65, v244, v65, s[6:7]
	v_cmp_le_u32_e64 s[6:7], v222, v219
	v_add_u32_e32 v222, 0x62, v221
	v_cmp_le_u32_e64 s[8:9], v222, v219
	v_add_u32_e32 v222, 0x43, v221
	s_nop 0
	v_cndmask_b32_e64 v66, v244, v66, s[8:9]
	v_cmp_le_u32_e64 s[8:9], v222, v219
	v_add_u32_e32 v222, 0x63, v221
	v_cmp_le_u32_e64 s[10:11], v222, v219
	v_add_u32_e32 v222, 0x48, v221
	s_nop 0
	v_cndmask_b32_e64 v67, v244, v67, s[10:11]
	v_cmp_le_u32_e64 s[10:11], v222, v219
	v_add_u32_e32 v222, 0x68, v221
	v_cmp_le_u32_e64 s[12:13], v222, v219
	v_add_u32_e32 v222, 0x49, v221
	s_nop 0
	v_cndmask_b32_e64 v68, v244, v68, s[12:13]
	v_cmp_le_u32_e64 s[12:13], v222, v219
	v_add_u32_e32 v222, 0x69, v221
	v_cmp_le_u32_e64 s[14:15], v222, v219
	v_add_u32_e32 v222, 0x4a, v221
	s_nop 0
	v_cndmask_b32_e64 v69, v244, v69, s[14:15]
	v_cmp_le_u32_e64 s[14:15], v222, v219
	v_add_u32_e32 v222, 0x6a, v221
	v_cmp_le_u32_e64 s[16:17], v222, v219
	v_add_u32_e32 v222, 0x4b, v221
	s_nop 0
	v_cndmask_b32_e64 v70, v244, v70, s[16:17]
	v_cmp_le_u32_e64 s[16:17], v222, v219
	v_add_u32_e32 v222, 0x6b, v221
	v_cmp_le_u32_e64 s[18:19], v222, v219
	v_add_u32_e32 v222, 0x50, v221
	s_nop 0
	v_cndmask_b32_e64 v71, v244, v71, s[18:19]
	v_cmp_le_u32_e64 s[18:19], v222, v219
	v_add_u32_e32 v222, 0x70, v221
	v_cmp_le_u32_e64 s[20:21], v222, v219
	v_add_u32_e32 v222, 0x51, v221
	s_nop 0
	v_cndmask_b32_e64 v72, v244, v72, s[20:21]
	v_cmp_le_u32_e64 s[20:21], v222, v219
	v_add_u32_e32 v222, 0x71, v221
	v_cmp_le_u32_e64 s[22:23], v222, v219
	v_add_u32_e32 v222, 0x52, v221
	s_nop 0
	v_cndmask_b32_e64 v73, v244, v73, s[22:23]
	v_cmp_le_u32_e64 s[22:23], v222, v219
	v_add_u32_e32 v222, 0x72, v221
	v_cmp_le_u32_e64 s[24:25], v222, v219
	v_add_u32_e32 v222, 0x53, v221
	s_nop 0
	v_cndmask_b32_e64 v74, v244, v74, s[24:25]
	v_cmp_le_u32_e64 s[24:25], v222, v219
	v_add_u32_e32 v222, 0x73, v221
	v_cmp_le_u32_e64 s[26:27], v222, v219
	v_add_u32_e32 v222, 0x58, v221
	s_nop 0
	v_cndmask_b32_e64 v75, v244, v75, s[26:27]
; __device__ __forceinline__ void sm_pv(f32x16& s0, f32x16& s1, f32x16& o0, f32x16& o1, float& m_run, float& l_run, f32x16& negm, LAS unsigned char* vb, bool domask, int kbase, int qm, int r32, int hi) {
;     ...
;     if (domask) {
;         const int kb0 = kbase + 4 * hi;
; #pragma unroll
;         for (int r = 0; r < 16; ++r) { const int kv = kb0 + (r & 3) + 8 * (r >> 2); if (kv > qm) s0[r] = -INFINITY; if (kv + 32 > qm) s1[r] = -INFINITY; }
;     }
;     float ma = fmaxf(fmaxf(s0[0], s0[1]), s1[0]), mb = fmaxf(fmaxf(s0[2], s0[3]), s1[1]);
;     ma = fmaxf(fmaxf(ma, s1[2]), s1[3]);
; #pragma unroll
;     for (int r = 4; r < 16; r += 4) { ma = fmaxf(fmaxf(ma, s0[r]), s0[r + 1]); mb = fmaxf(fmaxf(mb, s0[r + 2]), s0[r + 3]); ma = fmaxf(fmaxf(ma, s1[r]), s1[r + 1]); mb = fmaxf(fmaxf(mb, s1[r + 2]), s1[r + 3]); }
;     float mx = fmaxf(ma, mb);
;     { const auto rr = __builtin_amdgcn_permlane32_swap(__float_as_uint(mx), __float_as_uint(mx), false, false); mx = fmaxf(__uint_as_float(rr[0]), __uint_as_float(rr[1])); }
;     if (__builtin_amdgcn_ballot_w64(mx > 8.0f) != 0ull) {
;         const float d = fmaxf(mx, 0.0f);
;         const float alpha = __builtin_amdgcn_exp2f(-d);
;         m_run += d; l_run *= alpha; o0 = o0 * alpha; o1 = o1 * alpha;
;         s0 = s0 - d; s1 = s1 - d;
; #pragma unroll
;         for (int r = 0; r < 16; ++r) negm[r] = -m_run;
;     }
	v_cmp_le_u32_e64 s[26:27], v222, v219
	v_add_u32_e32 v222, 0x78, v221
	v_cmp_le_u32_e64 s[28:29], v222, v219
	v_add_u32_e32 v222, 0x59, v221
	s_nop 0
	v_cndmask_b32_e64 v76, v244, v76, s[28:29]
	v_cmp_le_u32_e64 s[28:29], v222, v219
	v_add_u32_e32 v222, 0x79, v221
	v_cmp_le_u32_e64 s[30:31], v222, v219
	v_add_u32_e32 v222, 0x5a, v221
	s_nop 0
	v_cndmask_b32_e64 v77, v244, v77, s[30:31]
	v_cmp_le_u32_e64 s[30:31], v222, v219
	v_add_u32_e32 v222, 0x7a, v221
	v_cmp_le_u32_e64 s[34:35], v222, v219
	v_add_u32_e32 v222, 0x5b, v221
	v_add_u32_e32 v221, 0x7b, v221
	v_cndmask_b32_e64 v78, v244, v78, s[34:35]
	v_cmp_le_u32_e64 s[34:35], v222, v219
	v_cmp_gt_u32_e64 s[36:37], v221, v219
	s_and_saveexec_b64 s[40:41], s[36:37]
	v_mov_b32_e32 v79, s52
	s_or_b64 exec, exec, s[40:41]
	v_cndmask_b32_e64 v81, v244, v81, s[4:5]
	v_cndmask_b32_e32 v80, v244, v80, vcc
	v_cndmask_b32_e64 v82, v244, v82, s[6:7]
	v_cndmask_b32_e64 v83, v244, v83, s[8:9]
	v_cndmask_b32_e64 v84, v244, v84, s[10:11]
	v_cndmask_b32_e64 v85, v244, v85, s[12:13]
	v_cndmask_b32_e64 v86, v244, v86, s[14:15]
	v_cndmask_b32_e64 v87, v244, v87, s[16:17]
	v_cndmask_b32_e64 v88, v244, v88, s[18:19]
	v_cndmask_b32_e64 v89, v244, v89, s[20:21]
	v_cndmask_b32_e64 v90, v244, v90, s[22:23]
	v_cndmask_b32_e64 v91, v244, v91, s[24:25]
	v_cndmask_b32_e64 v92, v244, v92, s[26:27]
	v_cndmask_b32_e64 v93, v244, v93, s[28:29]
	v_cndmask_b32_e64 v94, v244, v94, s[30:31]
	v_cndmask_b32_e64 v95, v244, v95, s[34:35]
.LBB0_434:
	s_or_b64 exec, exec, s[46:47]
	s_nop 6
	v_max_f32_e32 v221, v80, v81
	v_max3_f32 v222, v82, v83, v65
	v_max3_f32 v221, v221, v64, v66
	v_max3_f32 v221, v221, v67, v84
	v_max3_f32 v222, v222, v86, v87
	v_max3_f32 v221, v221, v85, v68
	v_max3_f32 v222, v222, v70, v71
	v_max3_f32 v221, v221, v69, v88
	v_max3_f32 v222, v222, v90, v91
	v_max3_f32 v221, v221, v89, v72
	v_max3_f32 v222, v222, v74, v75
	v_max3_f32 v221, v221, v73, v92
	v_max3_f32 v222, v222, v94, v95
	v_max3_f32 v221, v221, v93, v76
	v_max3_f32 v222, v222, v78, v79
	v_max3_f32 v221, v221, v77, v222
	v_mov_b32_e32 v222, v221
	s_nop 1
	v_permlane32_swap_b32_e32 v221, v222
	v_max_f32_e32 v221, v221, v222
	v_cmp_lt_f32_e32 vcc, s53, v221
	s_cbranch_vccz .LBB0_436
	v_max_f32_e32 v48, v221, v221
	v_max_f32_e32 v49, 0, v48
	v_exp_f32_e64 v48, -v49
	v_add_f32_e32 v1, v1, v49
	v_sub_f32_e32 v80, v80, v49
	v_sub_f32_e32 v81, v81, v49
	v_mul_f32_e32 v218, v218, v48
	v_pk_mul_f32 v[46:47], v[46:47], v[48:49] op_sel_hi:[1,0]
	v_pk_mul_f32 v[44:45], v[44:45], v[48:49] op_sel_hi:[1,0]
	v_pk_mul_f32 v[42:43], v[42:43], v[48:49] op_sel_hi:[1,0]
	v_pk_mul_f32 v[40:41], v[40:41], v[48:49] op_sel_hi:[1,0]
	v_pk_mul_f32 v[38:39], v[38:39], v[48:49] op_sel_hi:[1,0]
	v_pk_mul_f32 v[36:37], v[36:37], v[48:49] op_sel_hi:[1,0]
	v_pk_mul_f32 v[34:35], v[34:35], v[48:49] op_sel_hi:[1,0]
	v_pk_mul_f32 v[32:33], v[32:33], v[48:49] op_sel_hi:[1,0]
	v_pk_mul_f32 v[30:31], v[30:31], v[48:49] op_sel_hi:[1,0]
	v_pk_mul_f32 v[28:29], v[28:29], v[48:49] op_sel_hi:[1,0]
	v_pk_mul_f32 v[26:27], v[26:27], v[48:49] op_sel_hi:[1,0]
	v_pk_mul_f32 v[24:25], v[24:25], v[48:49] op_sel_hi:[1,0]
	v_pk_mul_f32 v[22:23], v[22:23], v[48:49] op_sel_hi:[1,0]
	v_pk_mul_f32 v[20:21], v[20:21], v[48:49] op_sel_hi:[1,0]
	v_pk_mul_f32 v[18:19], v[18:19], v[48:49] op_sel_hi:[1,0]
	v_pk_mul_f32 v[16:17], v[16:17], v[48:49] op_sel_hi:[1,0]
	v_xor_b32_e32 v48, 0x80000000, v1
	v_sub_f32_e32 v82, v82, v49
	v_sub_f32_e32 v83, v83, v49
	v_sub_f32_e32 v84, v84, v49
	v_sub_f32_e32 v85, v85, v49
	v_sub_f32_e32 v86, v86, v49
	v_sub_f32_e32 v87, v87, v49
	v_sub_f32_e32 v88, v88, v49
	v_sub_f32_e32 v89, v89, v49
	v_sub_f32_e32 v90, v90, v49
	v_sub_f32_e32 v91, v91, v49
	v_sub_f32_e32 v92, v92, v49
	v_sub_f32_e32 v93, v93, v49
	v_sub_f32_e32 v94, v94, v49
	v_sub_f32_e32 v95, v95, v49
	v_sub_f32_e32 v64, v64, v49
	v_sub_f32_e32 v65, v65, v49
	v_sub_f32_e32 v66, v66, v49
	v_sub_f32_e32 v67, v67, v49
	v_sub_f32_e32 v68, v68, v49
	v_sub_f32_e32 v69, v69, v49
	v_sub_f32_e32 v70, v70, v49
	v_sub_f32_e32 v71, v71, v49
	v_sub_f32_e32 v72, v72, v49
	v_sub_f32_e32 v73, v73, v49
	v_sub_f32_e32 v74, v74, v49
	v_sub_f32_e32 v75, v75, v49
	v_sub_f32_e32 v76, v76, v49
	v_sub_f32_e32 v77, v77, v49
	v_sub_f32_e32 v78, v78, v49
	v_sub_f32_e32 v79, v79, v49
	v_mov_b32_e32 v49, v48
	v_mov_b32_e32 v50, v48
	v_mov_b32_e32 v51, v48
	v_mov_b32_e32 v52, v48
	v_mov_b32_e32 v53, v48
	v_mov_b32_e32 v54, v48
	v_mov_b32_e32 v55, v48
	v_mov_b32_e32 v56, v48
	v_mov_b32_e32 v57, v48
	v_mov_b32_e32 v58, v48
	v_mov_b32_e32 v59, v48
	v_mov_b32_e32 v60, v48
	v_mov_b32_e32 v61, v48
	v_mov_b32_e32 v62, v48
	v_mov_b32_e32 v63, v48
; __device__ __forceinline__ unsigned cvtpk(float lo, float hi) { const f32x2 v = {lo, hi}; const bf16x2_t b = __builtin_convertvector(v, bf16x2_t); return __builtin_bit_cast(unsigned, b); }
; __device__ __forceinline__ void sm_pv(f32x16& s0, f32x16& s1, f32x16& o0, f32x16& o1, float& m_run, float& l_run, f32x16& negm, LAS unsigned char* vb, bool domask, int kbase, int qm, int r32, int hi) {
;     ...
;     f32x2 ps2 = (f32x2){0.f, 0.f};
; #pragma unroll
;     for (int r = 0; r < 16; r += 2) { s0[r] = __builtin_amdgcn_exp2f(s0[r]); s0[r + 1] = __builtin_amdgcn_exp2f(s0[r + 1]); s1[r] = __builtin_amdgcn_exp2f(s1[r]); s1[r + 1] = __builtin_amdgcn_exp2f(s1[r + 1]);
;         ps2 += (f32x2){s0[r], s0[r + 1]}; ps2 += (f32x2){s1[r], s1[r + 1]}; }
;     l_run += ps2[0] + ps2[1];
;     u32x4 pw[4];
; #pragma unroll
;     for (int i = 0; i < 4; ++i) { pw[0][i] = cvtpk(s0[2 * i], s0[2 * i + 1]); pw[1][i] = cvtpk(s0[8 + 2 * i], s0[8 + 2 * i + 1]); pw[2][i] = cvtpk(s1[2 * i], s1[2 * i + 1]); pw[3][i] = cvtpk(s1[8 + 2 * i], s1[8 + 2 * i + 1]); }
; #pragma unroll
;     for (int kk = 0; kk < 4; ++kk) {
;         const bf16x8 pf = __builtin_bit_cast(bf16x8, pw[kk]);
;         { const s16x4 lo = vlo[2 * kk], hh = vhh[2 * kk];
;           const bf16x8 vf = (bf16x8){lo[0], lo[1], lo[2], lo[3], hh[0], hh[1], hh[2], hh[3]};
;           o0 = __builtin_amdgcn_mfma_f32_32x32x16_bf16(vf, pf, o0, 0, 0, 0); }
;         { const s16x4 lo = vlo[2 * kk + 1], hh = vhh[2 * kk + 1];
;           const bf16x8 vf = (bf16x8){lo[0], lo[1], lo[2], lo[3], hh[0], hh[1], hh[2], hh[3]};
;           o1 = __builtin_amdgcn_mfma_f32_32x32x16_bf16(vf, pf, o1, 0, 0, 0); }
;     }
.LBB0_436:
	v_exp_f32_e32 v80, v80
	v_exp_f32_e32 v81, v81
	v_exp_f32_e32 v226, v82
	v_exp_f32_e32 v227, v83
	v_exp_f32_e32 v84, v84
	v_exp_f32_e32 v85, v85
	v_exp_f32_e32 v86, v86
	v_exp_f32_e32 v87, v87
	v_exp_f32_e32 v222, v64
	v_exp_f32_e32 v223, v65
	v_add_f32_e32 v64, 0, v80
	v_add_f32_e32 v65, 0, v81
	v_cvt_pk_bf16_f32 v80, v80, v81
	v_cvt_pk_bf16_f32 v81, v226, v227
	v_cvt_pk_bf16_f32 v82, v84, v85
	v_cvt_pk_bf16_f32 v83, v86, v87
	v_exp_f32_e32 v88, v88
	v_exp_f32_e32 v89, v89
	s_waitcnt lgkmcnt(6)
	v_mfma_f32_32x32x16_bf16 v[32:47], v[160:163], v[80:83], v[32:47]
	v_exp_f32_e32 v90, v90
	v_exp_f32_e32 v91, v91
	v_exp_f32_e32 v92, v92
	v_exp_f32_e32 v93, v93
	v_add_f32_e32 v224, v222, v64
	v_add_f32_e32 v225, v223, v65
	v_exp_f32_e32 v228, v66
	v_exp_f32_e32 v229, v67
	s_waitcnt lgkmcnt(5)
	v_mfma_f32_32x32x16_bf16 v[16:31], v[156:159], v[80:83], v[16:31]
	v_exp_f32_e32 v80, v94
	v_exp_f32_e32 v81, v95
	v_cvt_pk_bf16_f32 v64, v88, v89
	v_cvt_pk_bf16_f32 v65, v90, v91
	v_cvt_pk_bf16_f32 v66, v92, v93
	v_cvt_pk_bf16_f32 v67, v80, v81
	v_exp_f32_e32 v68, v68
	v_exp_f32_e32 v69, v69
	v_mfma_f32_32x32x16_bf16 v[32:47], v[152:155], v[64:67], v[32:47]
	v_exp_f32_e32 v70, v70
	v_exp_f32_e32 v71, v71
	v_add_f32_e32 v82, v226, v224
	v_add_f32_e32 v83, v227, v225
	v_exp_f32_e32 v72, v72
	v_add_f32_e32 v82, v228, v82
	v_add_f32_e32 v83, v229, v83
	v_exp_f32_e32 v73, v73
	v_add_f32_e32 v82, v84, v82
	v_add_f32_e32 v83, v85, v83
	s_waitcnt lgkmcnt(4)
	v_mfma_f32_32x32x16_bf16 v[16:31], v[148:151], v[64:67], v[16:31]
	v_cvt_pk_bf16_f32 v64, v222, v223
	v_cvt_pk_bf16_f32 v65, v228, v229
	v_cvt_pk_bf16_f32 v66, v68, v69
	v_cvt_pk_bf16_f32 v67, v70, v71
	v_add_f32_e64 v82, v68, v82
	v_add_f32_e64 v83, v69, v83
	v_add_f32_e32 v82, v86, v82
	v_add_f32_e32 v83, v87, v83
	s_waitcnt lgkmcnt(3)
	v_mfma_f32_32x32x16_bf16 v[32:47], v[144:147], v[64:67], v[32:47]
	v_add_f32_e64 v68, v70, v82
	v_add_f32_e64 v69, v71, v83
	v_exp_f32_e32 v70, v74
	v_exp_f32_e32 v71, v75
	v_exp_f32_e32 v74, v76
	v_exp_f32_e32 v75, v77
	v_exp_f32_e32 v76, v78
	v_exp_f32_e32 v77, v79
	s_waitcnt lgkmcnt(2)
	v_mfma_f32_32x32x16_bf16 v[16:31], v[140:143], v[64:67], v[16:31]
	v_add_f32_e64 v68, v88, v68
	v_add_f32_e64 v69, v89, v69
	v_cvt_pk_bf16_f32 v64, v72, v73
	v_add_f32_e64 v68, v72, v68
	v_add_f32_e64 v69, v73, v69
	v_cvt_pk_bf16_f32 v65, v70, v71
	v_cvt_pk_bf16_f32 v66, v74, v75
	v_cvt_pk_bf16_f32 v67, v76, v77
	v_add_f32_e32 v68, v90, v68
	v_add_f32_e32 v69, v91, v69
	s_waitcnt lgkmcnt(1)
	v_mfma_f32_32x32x16_bf16 v[32:47], v[136:139], v[64:67], v[32:47]
	v_add_f32_e64 v68, v70, v68
	v_add_f32_e64 v69, v71, v69
	v_add_f32_e64 v68, v92, v68
	v_add_f32_e64 v69, v93, v69
	v_add_f32_e64 v68, v74, v68
	v_add_f32_e64 v69, v75, v69
	v_add_f32_e32 v68, v80, v68
	v_add_f32_e32 v69, v81, v69
	s_waitcnt lgkmcnt(0)
	v_mfma_f32_32x32x16_bf16 v[16:31], v[10:13], v[64:67], v[16:31]
	v_add_f32_e64 v68, v76, v68
	v_add_f32_e64 v69, v77, v69
	v_add_f32_e32 v68, v68, v69
	v_add_f32_e32 v218, v218, v68

.LBB0_441:
	s_or_b64 exec, exec, s[4:5]
	s_waitcnt vmcnt(4)
	v_perm_b32 v2, v186, v184, s94
	v_perm_b32 v3, v186, v184, s95
	ds_write2_b32 v214, v2, v3 offset1:34
	v_perm_b32 v2, v187, v185, s94
	v_perm_b32 v3, v187, v185, s95
	ds_write2_b32 v214, v2, v3 offset0:68 offset1:102
	s_waitcnt lgkmcnt(0)
	s_barrier

; #define LAS __attribute__((address_space(3)))
; __device__ __forceinline__ void qk_tile(f32x16& s0, f32x16& s1, LAS unsigned char* kb, const bf16x8 (&qr)[6], const f32x16& negm, int r32, int hi) {
;     bf16x8 kf[12];
; #pragma unroll
;     for (int ks = 0; ks < 6; ++ks) { kf[2 * ks] = *(const LAS bf16x8*)(kb + r32 * KPT + ks * 32 + hi * 16); kf[2 * ks + 1] = *(const LAS bf16x8*)(kb + (32 + r32) * KPT + ks * 32 + hi * 16); }
;     __builtin_amdgcn_sched_barrier(0);
; #pragma unroll
;     for (int ks = 0; ks < 6; ++ks) {
;         s0 = __builtin_amdgcn_mfma_f32_32x32x16_bf16(kf[2 * ks], qr[ks], ks == 0 ? negm : s0, 0, 0, 0);
;         s1 = __builtin_amdgcn_mfma_f32_32x32x16_bf16(kf[2 * ks + 1], qr[ks], ks == 0 ? negm : s1, 0, 0, 0);
;     }
; }
; __device__ __forceinline__ void sm_pv(f32x16& s0, f32x16& s1, f32x16& o0, f32x16& o1, float& m_run, float& l_run, f32x16& negm, LAS unsigned char* vb, bool domask, int kbase, int qm, int r32, int hi) {
;     s16x4 vlo[8], vhh[8];
; #pragma unroll
;     for (int kk = 0; kk < 4; ++kk) { const int koff = 2 * (16 * kk + 4 * hi);
;         vlo[2 * kk] = *(const LAS s16x4*)(vb + r32 * VP + koff); vhh[2 * kk] = *(const LAS s16x4*)(vb + r32 * VP + koff + 16);
;         vlo[2 * kk + 1] = *(const LAS s16x4*)(vb + (32 + r32) * VP + koff); vhh[2 * kk + 1] = *(const LAS s16x4*)(vb + (32 + r32) * VP + koff + 16); }
;     __builtin_amdgcn_sched_barrier(0);
;     if (domask) {
;         const int kb0 = kbase + 4 * hi;
; #pragma unroll
;         for (int r = 0; r < 16; ++r) { const int kv = kb0 + (r & 3) + 8 * (r >> 2); if (kv > qm) s0[r] = -INFINITY; if (kv + 32 > qm) s1[r] = -INFINITY; }
.LBB0_443:
	s_add_i32 s85, s84, -3
	s_cmp_lt_u32 s85, s57
	s_cselect_b64 s[44:45], -1, 0
	s_and_b64 s[4:5], s[44:45], exec
	s_cselect_b32 s4, 0, s79
	s_lshl_b32 s4, s4, 6
	s_sub_i32 s5, 0x80, s4
	v_add_u32_e32 v14, s83, v213
	v_add_u32_e32 v15, s83, v173
	v_add_u32_e32 v2, s5, v14
	v_add_u32_e32 v3, s5, v15
	v_min_u32_e32 v2, 0x80ff, v2
	v_add_u32_e32 v5, 1, v3
	v_min_u32_e32 v3, 0x80ff, v3
	v_min_u32_e32 v5, 0x80ff, v5
	v_lshl_add_u32 v4, v2, 12, v238
	v_lshl_add_u32 v2, v2, 6, v239
	v_lshl_add_u32 v3, v3, 12, v174
	v_lshl_add_u32 v5, v5, 12, v174
	global_load_dwordx4 v[120:123], v4, s[98:99]
	global_load_dwordx4 v[124:127], v2, s[100:101]
	global_load_dwordx2 v[184:185], v3, s[98:99] offset:128
	global_load_dwordx2 v[186:187], v5, s[98:99] offset:128
	v_cmp_le_u32_e32 vcc, s83, v220
	s_and_saveexec_b64 s[46:47], vcc
	s_cbranch_execz .LBB0_451
	ds_read_b128 v[2:5], v241
	ds_read_b128 v[6:9], v241 offset:32
	ds_read_b128 v[10:13], v241 offset:6656
	ds_read_b128 v[136:139], v241 offset:6688
	ds_read_b128 v[140:143], v241 offset:64
	ds_read_b128 v[144:147], v241 offset:96
	ds_read_b128 v[148:151], v241 offset:6720
	ds_read_b128 v[152:155], v241 offset:6752
	ds_read_b128 v[156:159], v241 offset:128
	ds_read_b128 v[160:163], v241 offset:160
	ds_read_b128 v[222:225], v241 offset:6784
	ds_read_b128 v[226:229], v241 offset:6816
	s_waitcnt lgkmcnt(11)
	v_mfma_f32_32x32x16_bf16 v[80:95], v[2:5], v[96:99], v[48:63]
	s_add_i32 s4, s83, 63
	v_cmp_gt_i32_e32 vcc, s4, v175
	s_waitcnt lgkmcnt(9)
	v_mfma_f32_32x32x16_bf16 v[64:79], v[10:13], v[96:99], v[48:63]
	v_mfma_f32_32x32x16_bf16 v[80:95], v[6:9], v[100:103], v[80:95]
	s_waitcnt lgkmcnt(8)
	v_mfma_f32_32x32x16_bf16 v[64:79], v[136:139], v[100:103], v[64:79]
	s_waitcnt lgkmcnt(7)
	v_mfma_f32_32x32x16_bf16 v[80:95], v[140:143], v[104:107], v[80:95]
	s_waitcnt lgkmcnt(5)
	v_mfma_f32_32x32x16_bf16 v[64:79], v[148:151], v[104:107], v[64:79]
	v_mfma_f32_32x32x16_bf16 v[80:95], v[144:147], v[108:111], v[80:95]
	ds_read2_b64 v[144:147], v252 offset0:4 offset1:6
	s_waitcnt lgkmcnt(5)
	v_mfma_f32_32x32x16_bf16 v[64:79], v[152:155], v[108:111], v[64:79]
	ds_read2_b64 v[152:155], v252 offset1:2
	ds_read2_b64 v[148:151], v253 offset0:32 offset1:34
	ds_read2_b64 v[140:143], v253 offset0:36 offset1:38
	ds_read2_b64 v[136:139], v252 offset0:8 offset1:10
	ds_read2_b64 v[10:13], v253 offset0:40 offset1:42
	ds_read2_b64 v[6:9], v252 offset0:12 offset1:14
	ds_read2_b64 v[2:5], v253 offset0:44 offset1:46
	s_waitcnt lgkmcnt(11)
	v_mfma_f32_32x32x16_bf16 v[80:95], v[156:159], v[112:115], v[80:95]
	s_waitcnt lgkmcnt(9)
	v_mfma_f32_32x32x16_bf16 v[64:79], v[222:225], v[112:115], v[64:79]
	v_mfma_f32_32x32x16_bf16 v[80:95], v[160:163], v[116:119], v[80:95]
	s_waitcnt lgkmcnt(8)
	v_mfma_f32_32x32x16_bf16 v[64:79], v[226:229], v[116:119], v[64:79]
	s_and_saveexec_b64 s[58:59], vcc
	s_cbranch_execz .LBB0_448
	v_add_u32_e32 v156, s83, v201
	v_add_u32_e32 v157, 32, v156
	v_cmp_ge_i32_e64 s[4:5], v177, v157
	v_add_u32_e32 v157, 33, v156
	v_cmp_ge_i32_e64 s[6:7], v177, v157
	v_add_u32_e32 v157, 2, v156
	v_cmp_le_u32_e32 vcc, v156, v219
	s_nop 2
	v_cndmask_b32_e64 v65, v244, v65, s[6:7]
	v_cmp_ge_i32_e64 s[6:7], v177, v157
	v_add_u32_e32 v157, 34, v156
	v_cmp_ge_i32_e64 s[8:9], v177, v157
	v_add_u32_e32 v157, 3, v156
	v_cndmask_b32_e64 v64, v244, v64, s[4:5]
	v_cndmask_b32_e64 v66, v244, v66, s[8:9]
	v_cmp_ge_i32_e64 s[8:9], v177, v157
	v_add_u32_e32 v157, 35, v156
	v_cmp_ge_i32_e64 s[10:11], v177, v157
	v_add_u32_e32 v157, 8, v156
	v_cmp_gt_i32_e64 s[4:5], v177, v156
	v_cndmask_b32_e64 v67, v244, v67, s[10:11]
	v_cmp_ge_i32_e64 s[10:11], v177, v157
	v_add_u32_e32 v157, 40, v156
	v_cmp_ge_i32_e64 s[12:13], v177, v157
	v_add_u32_e32 v157, 9, v156
	s_nop 0
	v_cndmask_b32_e64 v68, v244, v68, s[12:13]
	v_cmp_ge_i32_e64 s[12:13], v177, v157
	v_add_u32_e32 v157, 41, v156
	v_cmp_ge_i32_e64 s[14:15], v177, v157
	v_add_u32_e32 v157, 10, v156
	s_nop 0
	v_cndmask_b32_e64 v69, v244, v69, s[14:15]
	v_cmp_ge_i32_e64 s[14:15], v177, v157
	v_add_u32_e32 v157, 42, v156
	v_cmp_ge_i32_e64 s[16:17], v177, v157
	v_add_u32_e32 v157, 11, v156
	s_nop 0
	v_cndmask_b32_e64 v70, v244, v70, s[16:17]
	v_cmp_ge_i32_e64 s[16:17], v177, v157
	v_add_u32_e32 v157, 43, v156
	v_cmp_ge_i32_e64 s[18:19], v177, v157
	v_add_u32_e32 v157, 16, v156
	s_nop 0
	v_cndmask_b32_e64 v71, v244, v71, s[18:19]
	v_cmp_ge_i32_e64 s[18:19], v177, v157
	v_add_u32_e32 v157, 48, v156
	v_cmp_ge_i32_e64 s[20:21], v177, v157
	v_add_u32_e32 v157, 17, v156
	s_nop 0
	v_cndmask_b32_e64 v72, v244, v72, s[20:21]
	v_cmp_ge_i32_e64 s[20:21], v177, v157
	v_add_u32_e32 v157, 49, v156
	v_cmp_ge_i32_e64 s[22:23], v177, v157
	v_add_u32_e32 v157, 18, v156
	s_nop 0
	v_cndmask_b32_e64 v73, v244, v73, s[22:23]
	v_cmp_ge_i32_e64 s[22:23], v177, v157
	v_add_u32_e32 v157, 50, v156
	v_cmp_ge_i32_e64 s[24:25], v177, v157
	v_add_u32_e32 v157, 19, v156
	s_nop 0
	v_cndmask_b32_e64 v74, v244, v74, s[24:25]
	v_cmp_ge_i32_e64 s[24:25], v177, v157
	v_add_u32_e32 v157, 51, v156
	v_cmp_ge_i32_e64 s[26:27], v177, v157
	v_add_u32_e32 v157, 24, v156
	s_nop 0
	v_cndmask_b32_e64 v75, v244, v75, s[26:27]
	v_cmp_ge_i32_e64 s[26:27], v177, v157
	v_add_u32_e32 v157, 56, v156
	v_cmp_ge_i32_e64 s[28:29], v177, v157
	v_add_u32_e32 v157, 25, v156
	s_nop 0
	v_cndmask_b32_e64 v76, v244, v76, s[28:29]
	v_cmp_ge_i32_e64 s[28:29], v177, v157
	v_add_u32_e32 v157, 57, v156
	v_cmp_ge_i32_e64 s[30:31], v177, v157
	v_add_u32_e32 v157, 26, v156
	s_nop 0
	v_cndmask_b32_e64 v77, v244, v77, s[30:31]
	v_cmp_ge_i32_e64 s[30:31], v177, v157
	v_add_u32_e32 v157, 58, v156
	v_cmp_ge_i32_e64 s[34:35], v177, v157
	v_add_u32_e32 v157, 27, v156
	v_add_u32_e32 v156, 59, v156
	v_cndmask_b32_e64 v78, v244, v78, s[34:35]
	v_cmp_ge_i32_e64 s[34:35], v177, v157
	v_cmp_lt_i32_e64 s[36:37], v177, v156
	s_and_saveexec_b64 s[40:41], s[36:37]
	v_mov_b32_e32 v79, s52
	s_or_b64 exec, exec, s[40:41]
	v_cndmask_b32_e32 v80, v244, v80, vcc
	v_cndmask_b32_e64 v81, v244, v81, s[4:5]
	v_cndmask_b32_e64 v82, v244, v82, s[6:7]
	v_cndmask_b32_e64 v83, v244, v83, s[8:9]
	v_cndmask_b32_e64 v84, v244, v84, s[10:11]
	v_cndmask_b32_e64 v85, v244, v85, s[12:13]
	v_cndmask_b32_e64 v86, v244, v86, s[14:15]
	v_cndmask_b32_e64 v87, v244, v87, s[16:17]
	v_cndmask_b32_e64 v88, v244, v88, s[18:19]
	v_cndmask_b32_e64 v89, v244, v89, s[20:21]
	v_cndmask_b32_e64 v90, v244, v90, s[22:23]
	v_cndmask_b32_e64 v91, v244, v91, s[24:25]
	v_cndmask_b32_e64 v92, v244, v92, s[26:27]
	v_cndmask_b32_e64 v93, v244, v93, s[28:29]
	v_cndmask_b32_e64 v94, v244, v94, s[30:31]
	v_cndmask_b32_e64 v95, v244, v95, s[34:35]
; __device__ __forceinline__ void sm_pv(f32x16& s0, f32x16& s1, f32x16& o0, f32x16& o1, float& m_run, float& l_run, f32x16& negm, LAS unsigned char* vb, bool domask, int kbase, int qm, int r32, int hi) {
;     ...
;     float ma = fmaxf(fmaxf(s0[0], s0[1]), s1[0]), mb = fmaxf(fmaxf(s0[2], s0[3]), s1[1]);
;     ma = fmaxf(fmaxf(ma, s1[2]), s1[3]);
; #pragma unroll
;     for (int r = 4; r < 16; r += 4) { ma = fmaxf(fmaxf(ma, s0[r]), s0[r + 1]); mb = fmaxf(fmaxf(mb, s0[r + 2]), s0[r + 3]); ma = fmaxf(fmaxf(ma, s1[r]), s1[r + 1]); mb = fmaxf(fmaxf(mb, s1[r + 2]), s1[r + 3]); }
;     float mx = fmaxf(ma, mb);
;     { const auto rr = __builtin_amdgcn_permlane32_swap(__float_as_uint(mx), __float_as_uint(mx), false, false); mx = fmaxf(__uint_as_float(rr[0]), __uint_as_float(rr[1])); }
;     if (__builtin_amdgcn_ballot_w64(mx > 8.0f) != 0ull) {
;         const float d = fmaxf(mx, 0.0f);
;         const float alpha = __builtin_amdgcn_exp2f(-d);
;         m_run += d; l_run *= alpha; o0 = o0 * alpha; o1 = o1 * alpha;
;         s0 = s0 - d; s1 = s1 - d;
; #pragma unroll
;         for (int r = 0; r < 16; ++r) negm[r] = -m_run;
;     }
;     f32x2 ps2 = (f32x2){0.f, 0.f};
; #pragma unroll
;     for (int r = 0; r < 16; r += 2) { s0[r] = __builtin_amdgcn_exp2f(s0[r]); s0[r + 1] = __builtin_amdgcn_exp2f(s0[r + 1]); s1[r] = __builtin_amdgcn_exp2f(s1[r]); s1[r + 1] = __builtin_amdgcn_exp2f(s1[r + 1]);
;         ps2 += (f32x2){s0[r], s0[r + 1]}; ps2 += (f32x2){s1[r], s1[r + 1]}; }
;     l_run += ps2[0] + ps2[1];
;     u32x4 pw[4];
; #pragma unroll
;     for (int i = 0; i < 4; ++i) { pw[0][i] = cvtpk(s0[2 * i], s0[2 * i + 1]); pw[1][i] = cvtpk(s0[8 + 2 * i], s0[8 + 2 * i + 1]); pw[2][i] = cvtpk(s1[2 * i], s1[2 * i + 1]); pw[3][i] = cvtpk(s1[8 + 2 * i], s1[8 + 2 * i + 1]); }
; #pragma unroll
;     for (int kk = 0; kk < 4; ++kk) {
;         const bf16x8 pf = __builtin_bit_cast(bf16x8, pw[kk]);
;         { const s16x4 lo = vlo[2 * kk], hh = vhh[2 * kk];
;           const bf16x8 vf = (bf16x8){lo[0], lo[1], lo[2], lo[3], hh[0], hh[1], hh[2], hh[3]};
;           o0 = __builtin_amdgcn_mfma_f32_32x32x16_bf16(vf, pf, o0, 0, 0, 0); }
;         { const s16x4 lo = vlo[2 * kk + 1], hh = vhh[2 * kk + 1];
;           const bf16x8 vf = (bf16x8){lo[0], lo[1], lo[2], lo[3], hh[0], hh[1], hh[2], hh[3]};
;           o1 = __builtin_amdgcn_mfma_f32_32x32x16_bf16(vf, pf, o1, 0, 0, 0); }
;     }
.LBB0_448:
	s_or_b64 exec, exec, s[58:59]
	s_nop 6
	v_max_f32_e32 v156, v80, v81
	v_max3_f32 v157, v82, v83, v65
	v_max3_f32 v156, v156, v64, v66
	v_max3_f32 v156, v156, v67, v84
	v_max3_f32 v157, v157, v86, v87
	v_max3_f32 v156, v156, v85, v68
	v_max3_f32 v157, v157, v70, v71
	v_max3_f32 v156, v156, v69, v88
	v_max3_f32 v157, v157, v90, v91
	v_max3_f32 v156, v156, v89, v72
	v_max3_f32 v157, v157, v74, v75
	v_max3_f32 v156, v156, v73, v92
	v_max3_f32 v157, v157, v94, v95
	v_max3_f32 v156, v156, v93, v76
	v_max3_f32 v157, v157, v78, v79
	v_max3_f32 v156, v156, v77, v157
	v_mov_b32_e32 v157, v156
	s_nop 1
	v_permlane32_swap_b32_e32 v156, v157
	v_max_f32_e32 v156, v156, v157
	v_cmp_lt_f32_e32 vcc, s53, v156
	s_cbranch_vccz .LBB0_450
	v_max_f32_e32 v48, v156, v156
	v_max_f32_e32 v49, 0, v48
	v_exp_f32_e64 v48, -v49
	v_add_f32_e32 v1, v1, v49
	v_sub_f32_e32 v80, v80, v49
	v_sub_f32_e32 v81, v81, v49
	v_mul_f32_e32 v218, v218, v48
	v_pk_mul_f32 v[46:47], v[46:47], v[48:49] op_sel_hi:[1,0]
	v_pk_mul_f32 v[44:45], v[44:45], v[48:49] op_sel_hi:[1,0]
	v_pk_mul_f32 v[42:43], v[42:43], v[48:49] op_sel_hi:[1,0]
	v_pk_mul_f32 v[40:41], v[40:41], v[48:49] op_sel_hi:[1,0]
	v_pk_mul_f32 v[38:39], v[38:39], v[48:49] op_sel_hi:[1,0]
	v_pk_mul_f32 v[36:37], v[36:37], v[48:49] op_sel_hi:[1,0]
	v_pk_mul_f32 v[34:35], v[34:35], v[48:49] op_sel_hi:[1,0]
	v_pk_mul_f32 v[32:33], v[32:33], v[48:49] op_sel_hi:[1,0]
	v_pk_mul_f32 v[30:31], v[30:31], v[48:49] op_sel_hi:[1,0]
	v_pk_mul_f32 v[28:29], v[28:29], v[48:49] op_sel_hi:[1,0]
	v_pk_mul_f32 v[26:27], v[26:27], v[48:49] op_sel_hi:[1,0]
	v_pk_mul_f32 v[24:25], v[24:25], v[48:49] op_sel_hi:[1,0]
	v_pk_mul_f32 v[22:23], v[22:23], v[48:49] op_sel_hi:[1,0]
	v_pk_mul_f32 v[20:21], v[20:21], v[48:49] op_sel_hi:[1,0]
	v_pk_mul_f32 v[18:19], v[18:19], v[48:49] op_sel_hi:[1,0]
	v_pk_mul_f32 v[16:17], v[16:17], v[48:49] op_sel_hi:[1,0]
	v_xor_b32_e32 v48, 0x80000000, v1
	v_sub_f32_e32 v82, v82, v49
	v_sub_f32_e32 v83, v83, v49
	v_sub_f32_e32 v84, v84, v49
	v_sub_f32_e32 v85, v85, v49
	v_sub_f32_e32 v86, v86, v49
	v_sub_f32_e32 v87, v87, v49
	v_sub_f32_e32 v88, v88, v49
	v_sub_f32_e32 v89, v89, v49
	v_sub_f32_e32 v90, v90, v49
	v_sub_f32_e32 v91, v91, v49
	v_sub_f32_e32 v92, v92, v49
	v_sub_f32_e32 v93, v93, v49
	v_sub_f32_e32 v94, v94, v49
	v_sub_f32_e32 v95, v95, v49
	v_sub_f32_e32 v64, v64, v49
	v_sub_f32_e32 v65, v65, v49
	v_sub_f32_e32 v66, v66, v49
	v_sub_f32_e32 v67, v67, v49
	v_sub_f32_e32 v68, v68, v49
	v_sub_f32_e32 v69, v69, v49
	v_sub_f32_e32 v70, v70, v49
	v_sub_f32_e32 v71, v71, v49
	v_sub_f32_e32 v72, v72, v49
	v_sub_f32_e32 v73, v73, v49
	v_sub_f32_e32 v74, v74, v49
	v_sub_f32_e32 v75, v75, v49
	v_sub_f32_e32 v76, v76, v49
	v_sub_f32_e32 v77, v77, v49
	v_sub_f32_e32 v78, v78, v49
	v_sub_f32_e32 v79, v79, v49
	v_mov_b32_e32 v49, v48
	v_mov_b32_e32 v50, v48
	v_mov_b32_e32 v51, v48
	v_mov_b32_e32 v52, v48
	v_mov_b32_e32 v53, v48
	v_mov_b32_e32 v54, v48
	v_mov_b32_e32 v55, v48
	v_mov_b32_e32 v56, v48
	v_mov_b32_e32 v57, v48
	v_mov_b32_e32 v58, v48
	v_mov_b32_e32 v59, v48
	v_mov_b32_e32 v60, v48
	v_mov_b32_e32 v61, v48
	v_mov_b32_e32 v62, v48
	v_mov_b32_e32 v63, v48
.LBB0_450:
	v_exp_f32_e32 v80, v80
	v_exp_f32_e32 v81, v81
	v_exp_f32_e32 v160, v82
	v_exp_f32_e32 v161, v83
	v_exp_f32_e32 v84, v84
	v_exp_f32_e32 v85, v85
	v_exp_f32_e32 v86, v86
	v_exp_f32_e32 v87, v87
	v_exp_f32_e32 v156, v64
	v_exp_f32_e32 v157, v65
	v_add_f32_e32 v64, 0, v80
	v_add_f32_e32 v65, 0, v81
	v_cvt_pk_bf16_f32 v80, v80, v81
	v_cvt_pk_bf16_f32 v81, v160, v161
	v_cvt_pk_bf16_f32 v82, v84, v85
	v_cvt_pk_bf16_f32 v83, v86, v87
	v_exp_f32_e32 v88, v88
	v_exp_f32_e32 v89, v89
	s_waitcnt lgkmcnt(6)
	v_mfma_f32_32x32x16_bf16 v[32:47], v[152:155], v[80:83], v[32:47]
	v_exp_f32_e32 v90, v90
	v_exp_f32_e32 v91, v91
	v_exp_f32_e32 v92, v92
	v_exp_f32_e32 v93, v93
	v_add_f32_e32 v158, v156, v64
	v_add_f32_e32 v159, v157, v65
	v_exp_f32_e32 v162, v66
	v_exp_f32_e32 v163, v67
	s_waitcnt lgkmcnt(5)
	v_mfma_f32_32x32x16_bf16 v[16:31], v[148:151], v[80:83], v[16:31]
	v_exp_f32_e32 v80, v94
	v_exp_f32_e32 v81, v95
	v_cvt_pk_bf16_f32 v64, v88, v89
	v_cvt_pk_bf16_f32 v65, v90, v91
	v_cvt_pk_bf16_f32 v66, v92, v93
	v_cvt_pk_bf16_f32 v67, v80, v81
	v_exp_f32_e32 v68, v68
	v_exp_f32_e32 v69, v69
	v_mfma_f32_32x32x16_bf16 v[32:47], v[144:147], v[64:67], v[32:47]
	v_exp_f32_e32 v70, v70
	v_exp_f32_e32 v71, v71
	v_add_f32_e32 v82, v160, v158
	v_add_f32_e32 v83, v161, v159
	v_exp_f32_e32 v72, v72
	v_add_f32_e32 v82, v162, v82
	v_add_f32_e32 v83, v163, v83
	v_exp_f32_e32 v73, v73
	v_add_f32_e32 v82, v84, v82
	v_add_f32_e32 v83, v85, v83
	s_waitcnt lgkmcnt(4)
	v_mfma_f32_32x32x16_bf16 v[16:31], v[140:143], v[64:67], v[16:31]
	v_cvt_pk_bf16_f32 v64, v156, v157
	v_cvt_pk_bf16_f32 v65, v162, v163
	v_cvt_pk_bf16_f32 v66, v68, v69
	v_cvt_pk_bf16_f32 v67, v70, v71
	v_add_f32_e64 v82, v68, v82
	v_add_f32_e64 v83, v69, v83
	v_add_f32_e32 v82, v86, v82
	v_add_f32_e32 v83, v87, v83
	s_waitcnt lgkmcnt(3)
	v_mfma_f32_32x32x16_bf16 v[32:47], v[136:139], v[64:67], v[32:47]
	v_add_f32_e64 v68, v70, v82
	v_add_f32_e64 v69, v71, v83
	v_exp_f32_e32 v70, v74
	v_exp_f32_e32 v71, v75
	v_exp_f32_e32 v74, v76
	v_exp_f32_e32 v75, v77
	v_add_f32_e32 v68, v88, v68
	v_add_f32_e32 v69, v89, v69
	s_waitcnt lgkmcnt(2)
	v_mfma_f32_32x32x16_bf16 v[16:31], v[10:13], v[64:67], v[16:31]
	v_exp_f32_e32 v64, v78
	v_exp_f32_e32 v65, v79
	v_add_f32_e32 v68, v72, v68
	v_add_f32_e32 v69, v73, v69
	v_cvt_pk_bf16_f32 v10, v72, v73
	v_add_f32_e32 v68, v90, v68
	v_add_f32_e32 v69, v91, v69
	v_cvt_pk_bf16_f32 v11, v70, v71
	v_cvt_pk_bf16_f32 v12, v74, v75
	v_cvt_pk_bf16_f32 v13, v64, v65
	s_waitcnt lgkmcnt(1)
	s_nop 0
	v_mfma_f32_32x32x16_bf16 v[32:47], v[6:9], v[10:13], v[32:47]
	v_add_f32_e64 v6, v70, v68
	v_add_f32_e64 v7, v71, v69
	v_add_f32_e64 v6, v92, v6
	v_add_f32_e64 v7, v93, v7
	v_add_f32_e64 v6, v74, v6
	v_add_f32_e64 v7, v75, v7
	v_add_f32_e32 v6, v80, v6
	v_add_f32_e32 v7, v81, v7
	s_waitcnt lgkmcnt(0)
	v_mfma_f32_32x32x16_bf16 v[16:31], v[2:5], v[10:13], v[16:31]
	v_add_f32_e64 v6, v64, v6
	v_add_f32_e64 v7, v65, v7
	v_add_f32_e32 v6, v6, v7
	v_add_f32_e32 v218, v218, v6

; #define LAS __attribute__((address_space(3)))
; __device__ __forceinline__ void qk_tile(f32x16& s0, f32x16& s1, LAS unsigned char* kb, const bf16x8 (&qr)[6], const f32x16& negm, int r32, int hi) {
;     bf16x8 kf[12];
; #pragma unroll
;     for (int ks = 0; ks < 6; ++ks) { kf[2 * ks] = *(const LAS bf16x8*)(kb + r32 * KPT + ks * 32 + hi * 16); kf[2 * ks + 1] = *(const LAS bf16x8*)(kb + (32 + r32) * KPT + ks * 32 + hi * 16); }
;     __builtin_amdgcn_sched_barrier(0);
; #pragma unroll
;     for (int ks = 0; ks < 6; ++ks) {
;         s0 = __builtin_amdgcn_mfma_f32_32x32x16_bf16(kf[2 * ks], qr[ks], ks == 0 ? negm : s0, 0, 0, 0);
;         s1 = __builtin_amdgcn_mfma_f32_32x32x16_bf16(kf[2 * ks + 1], qr[ks], ks == 0 ? negm : s1, 0, 0, 0);
;     }
; }
; __device__ __forceinline__ void sm_pv(f32x16& s0, f32x16& s1, f32x16& o0, f32x16& o1, float& m_run, float& l_run, f32x16& negm, LAS unsigned char* vb, bool domask, int kbase, int qm, int r32, int hi) {
;     s16x4 vlo[8], vhh[8];
; #pragma unroll
;     for (int kk = 0; kk < 4; ++kk) { const int koff = 2 * (16 * kk + 4 * hi);
;         vlo[2 * kk] = *(const LAS s16x4*)(vb + r32 * VP + koff); vhh[2 * kk] = *(const LAS s16x4*)(vb + r32 * VP + koff + 16);
;         vlo[2 * kk + 1] = *(const LAS s16x4*)(vb + (32 + r32) * VP + koff); vhh[2 * kk + 1] = *(const LAS s16x4*)(vb + (32 + r32) * VP + koff + 16); }
;     __builtin_amdgcn_sched_barrier(0);
;     if (domask) {
;         const int kb0 = kbase + 4 * hi;
; #pragma unroll
;         for (int r = 0; r < 16; ++r) { const int kv = kb0 + (r & 3) + 8 * (r >> 2); if (kv > qm) s0[r] = -INFINITY; if (kv + 32 > qm) s1[r] = -INFINITY; }
.LBB0_453:
	s_or_b64 exec, exec, s[4:5]
	s_waitcnt vmcnt(4)
	v_perm_b32 v2, v190, v188, s94
	v_perm_b32 v3, v190, v188, s95
	ds_write2_b32 v254, v2, v3 offset0:128 offset1:162
	v_perm_b32 v2, v191, v189, s94
	v_perm_b32 v3, v191, v189, s95
	ds_write2_b32 v254, v2, v3 offset0:196 offset1:230
	s_waitcnt lgkmcnt(0)
	s_barrier
	s_andn2_b64 vcc, exec, s[44:45]
	s_cbranch_vccnz .LBB0_442
	s_cmp_gt_u32 s84, s57
	s_cselect_b32 s4, s79, 0
	s_lshl_b32 s4, s4, 6
	s_sub_i32 s4, 0xc0, s4
	v_add_u32_e32 v2, s4, v14
	v_add_u32_e32 v3, s4, v15
	v_min_u32_e32 v2, 0x80ff, v2
	v_add_u32_e32 v5, 1, v3
	v_min_u32_e32 v3, 0x80ff, v3
	v_min_u32_e32 v5, 0x80ff, v5
	v_lshl_add_u32 v4, v2, 12, v238
	v_lshl_add_u32 v2, v2, 6, v239
	v_lshl_add_u32 v3, v3, 12, v174
	v_lshl_add_u32 v5, v5, 12, v174
	global_load_dwordx4 v[128:131], v4, s[98:99]
	global_load_dwordx4 v[132:135], v2, s[100:101]
	global_load_dwordx2 v[188:189], v3, s[98:99] offset:128
	global_load_dwordx2 v[190:191], v5, s[98:99] offset:128
	s_add_i32 s4, s83, 64
	v_cmp_le_u32_e32 vcc, s4, v220
	s_and_saveexec_b64 s[44:45], vcc
	s_cbranch_execz .LBB0_462
	ds_read_b128 v[2:5], v240 offset:13312
	ds_read_b128 v[6:9], v240 offset:13344
	ds_read_b128 v[10:13], v240 offset:19968
	ds_read_b128 v[136:139], v240 offset:20000
	ds_read_b128 v[140:143], v240 offset:13376
	ds_read_b128 v[144:147], v240 offset:13408
	ds_read_b128 v[148:151], v240 offset:20032
	ds_read_b128 v[152:155], v240 offset:20064
	ds_read_b128 v[156:159], v240 offset:13440
	ds_read_b128 v[160:163], v240 offset:13472
	ds_read_b128 v[222:225], v240 offset:20096
	ds_read_b128 v[226:229], v240 offset:20128
	s_waitcnt lgkmcnt(11)
	v_mfma_f32_32x32x16_bf16 v[80:95], v[2:5], v[96:99], v[48:63]
	s_add_i32 s4, s83, 0x7f
	v_cmp_gt_i32_e32 vcc, s4, v175
	s_waitcnt lgkmcnt(9)
	v_mfma_f32_32x32x16_bf16 v[64:79], v[10:13], v[96:99], v[48:63]
	v_mfma_f32_32x32x16_bf16 v[80:95], v[6:9], v[100:103], v[80:95]
	s_waitcnt lgkmcnt(8)
	v_mfma_f32_32x32x16_bf16 v[64:79], v[136:139], v[100:103], v[64:79]
	s_waitcnt lgkmcnt(7)
	v_mfma_f32_32x32x16_bf16 v[80:95], v[140:143], v[104:107], v[80:95]
	s_waitcnt lgkmcnt(5)
	v_mfma_f32_32x32x16_bf16 v[64:79], v[148:151], v[104:107], v[64:79]
	v_mfma_f32_32x32x16_bf16 v[80:95], v[144:147], v[108:111], v[80:95]
	ds_read2_b64 v[144:147], v250 offset0:68 offset1:70
	s_waitcnt lgkmcnt(5)
	v_mfma_f32_32x32x16_bf16 v[64:79], v[152:155], v[108:111], v[64:79]
	ds_read2_b64 v[152:155], v250 offset0:64 offset1:66
	ds_read2_b64 v[148:151], v251 offset0:96 offset1:98
	ds_read2_b64 v[140:143], v251 offset0:100 offset1:102
	ds_read2_b64 v[136:139], v250 offset0:72 offset1:74
	ds_read2_b64 v[10:13], v251 offset0:104 offset1:106
	ds_read2_b64 v[6:9], v250 offset0:76 offset1:78
	ds_read2_b64 v[2:5], v251 offset0:108 offset1:110
	s_waitcnt lgkmcnt(11)
	v_mfma_f32_32x32x16_bf16 v[80:95], v[156:159], v[112:115], v[80:95]
	s_waitcnt lgkmcnt(9)
	v_mfma_f32_32x32x16_bf16 v[64:79], v[222:225], v[112:115], v[64:79]
	v_mfma_f32_32x32x16_bf16 v[80:95], v[160:163], v[116:119], v[80:95]
	s_waitcnt lgkmcnt(8)
	v_mfma_f32_32x32x16_bf16 v[64:79], v[226:229], v[116:119], v[64:79]
	s_and_saveexec_b64 s[46:47], vcc
	s_cbranch_execz .LBB0_459
	v_add_u32_e32 v14, s83, v201
	v_add_u32_e32 v156, 0x60, v14
	v_add_u32_e32 v15, 64, v14
	v_cmp_le_u32_e64 s[4:5], v156, v219
	v_cmp_le_u32_e32 vcc, v15, v219
	s_nop 4
	v_cndmask_b32_e64 v64, v244, v64, s[4:5]
	v_cmp_lt_u32_e64 s[4:5], v15, v219
	v_add_u32_e32 v15, 0x61, v14
	v_cmp_le_u32_e64 s[6:7], v15, v219
	v_add_u32_e32 v15, 0x42, v14
	s_nop 0
	v_cndmask_b32_e64 v65, v244, v65, s[6:7]
	v_cmp_le_u32_e64 s[6:7], v15, v219
	v_add_u32_e32 v15, 0x62, v14
	v_cmp_le_u32_e64 s[8:9], v15, v219
	v_add_u32_e32 v15, 0x43, v14
	s_nop 0
	v_cndmask_b32_e64 v66, v244, v66, s[8:9]
	v_cmp_le_u32_e64 s[8:9], v15, v219
	v_add_u32_e32 v15, 0x63, v14
	v_cmp_le_u32_e64 s[10:11], v15, v219
	v_add_u32_e32 v15, 0x48, v14
	s_nop 0
	v_cndmask_b32_e64 v67, v244, v67, s[10:11]
	v_cmp_le_u32_e64 s[10:11], v15, v219
	v_add_u32_e32 v15, 0x68, v14
	v_cmp_le_u32_e64 s[12:13], v15, v219
	v_add_u32_e32 v15, 0x49, v14
	s_nop 0
	v_cndmask_b32_e64 v68, v244, v68, s[12:13]
	v_cmp_le_u32_e64 s[12:13], v15, v219
	v_add_u32_e32 v15, 0x69, v14
	v_cmp_le_u32_e64 s[14:15], v15, v219
	v_add_u32_e32 v15, 0x4a, v14
	s_nop 0
	v_cndmask_b32_e64 v69, v244, v69, s[14:15]
	v_cmp_le_u32_e64 s[14:15], v15, v219
	v_add_u32_e32 v15, 0x6a, v14
	v_cmp_le_u32_e64 s[16:17], v15, v219
	v_add_u32_e32 v15, 0x4b, v14
	s_nop 0
	v_cndmask_b32_e64 v70, v244, v70, s[16:17]
	v_cmp_le_u32_e64 s[16:17], v15, v219
	v_add_u32_e32 v15, 0x6b, v14
	v_cmp_le_u32_e64 s[18:19], v15, v219
	v_add_u32_e32 v15, 0x50, v14
	s_nop 0
	v_cndmask_b32_e64 v71, v244, v71, s[18:19]
	v_cmp_le_u32_e64 s[18:19], v15, v219
	v_add_u32_e32 v15, 0x70, v14
	v_cmp_le_u32_e64 s[20:21], v15, v219
	v_add_u32_e32 v15, 0x51, v14
	s_nop 0
	v_cndmask_b32_e64 v72, v244, v72, s[20:21]
	v_cmp_le_u32_e64 s[20:21], v15, v219
	v_add_u32_e32 v15, 0x71, v14
	v_cmp_le_u32_e64 s[22:23], v15, v219
	v_add_u32_e32 v15, 0x52, v14
	s_nop 0
	v_cndmask_b32_e64 v73, v244, v73, s[22:23]
	v_cmp_le_u32_e64 s[22:23], v15, v219
	v_add_u32_e32 v15, 0x72, v14
	v_cmp_le_u32_e64 s[24:25], v15, v219
	v_add_u32_e32 v15, 0x53, v14
	s_nop 0
	v_cndmask_b32_e64 v74, v244, v74, s[24:25]
	v_cmp_le_u32_e64 s[24:25], v15, v219
	v_add_u32_e32 v15, 0x73, v14
	v_cmp_le_u32_e64 s[26:27], v15, v219
	v_add_u32_e32 v15, 0x58, v14
	s_nop 0
	v_cndmask_b32_e64 v75, v244, v75, s[26:27]
	v_cmp_le_u32_e64 s[26:27], v15, v219
	v_add_u32_e32 v15, 0x78, v14
	v_cmp_le_u32_e64 s[28:29], v15, v219
	v_add_u32_e32 v15, 0x59, v14
	s_nop 0
	v_cndmask_b32_e64 v76, v244, v76, s[28:29]
	v_cmp_le_u32_e64 s[28:29], v15, v219
	v_add_u32_e32 v15, 0x79, v14
	v_cmp_le_u32_e64 s[30:31], v15, v219
	v_add_u32_e32 v15, 0x5a, v14
	s_nop 0
	v_cndmask_b32_e64 v77, v244, v77, s[30:31]
	v_cmp_le_u32_e64 s[30:31], v15, v219
	v_add_u32_e32 v15, 0x7a, v14
	v_cmp_le_u32_e64 s[34:35], v15, v219
	v_add_u32_e32 v15, 0x5b, v14
	v_add_u32_e32 v14, 0x7b, v14
	v_cndmask_b32_e64 v78, v244, v78, s[34:35]
	v_cmp_le_u32_e64 s[34:35], v15, v219
	v_cmp_gt_u32_e64 s[36:37], v14, v219
	s_and_saveexec_b64 s[40:41], s[36:37]
	v_mov_b32_e32 v79, s52
	s_or_b64 exec, exec, s[40:41]
	v_cndmask_b32_e64 v81, v244, v81, s[4:5]
	v_cndmask_b32_e32 v80, v244, v80, vcc
	v_cndmask_b32_e64 v82, v244, v82, s[6:7]
	v_cndmask_b32_e64 v83, v244, v83, s[8:9]
	v_cndmask_b32_e64 v84, v244, v84, s[10:11]
	v_cndmask_b32_e64 v85, v244, v85, s[12:13]
	v_cndmask_b32_e64 v86, v244, v86, s[14:15]
	v_cndmask_b32_e64 v87, v244, v87, s[16:17]
	v_cndmask_b32_e64 v88, v244, v88, s[18:19]
	v_cndmask_b32_e64 v89, v244, v89, s[20:21]
	v_cndmask_b32_e64 v90, v244, v90, s[22:23]
	v_cndmask_b32_e64 v91, v244, v91, s[24:25]
	v_cndmask_b32_e64 v92, v244, v92, s[26:27]
	v_cndmask_b32_e64 v93, v244, v93, s[28:29]
	v_cndmask_b32_e64 v94, v244, v94, s[30:31]
	v_cndmask_b32_e64 v95, v244, v95, s[34:35]
; __device__ __forceinline__ void sm_pv(f32x16& s0, f32x16& s1, f32x16& o0, f32x16& o1, float& m_run, float& l_run, f32x16& negm, LAS unsigned char* vb, bool domask, int kbase, int qm, int r32, int hi) {
;     ...
;     float ma = fmaxf(fmaxf(s0[0], s0[1]), s1[0]), mb = fmaxf(fmaxf(s0[2], s0[3]), s1[1]);
;     ma = fmaxf(fmaxf(ma, s1[2]), s1[3]);
; #pragma unroll
;     for (int r = 4; r < 16; r += 4) { ma = fmaxf(fmaxf(ma, s0[r]), s0[r + 1]); mb = fmaxf(fmaxf(mb, s0[r + 2]), s0[r + 3]); ma = fmaxf(fmaxf(ma, s1[r]), s1[r + 1]); mb = fmaxf(fmaxf(mb, s1[r + 2]), s1[r + 3]); }
;     float mx = fmaxf(ma, mb);
;     { const auto rr = __builtin_amdgcn_permlane32_swap(__float_as_uint(mx), __float_as_uint(mx), false, false); mx = fmaxf(__uint_as_float(rr[0]), __uint_as_float(rr[1])); }
;     if (__builtin_amdgcn_ballot_w64(mx > 8.0f) != 0ull) {
;         const float d = fmaxf(mx, 0.0f);
;         const float alpha = __builtin_amdgcn_exp2f(-d);
;         m_run += d; l_run *= alpha; o0 = o0 * alpha; o1 = o1 * alpha;
;         s0 = s0 - d; s1 = s1 - d;
; #pragma unroll
;         for (int r = 0; r < 16; ++r) negm[r] = -m_run;
;     }
;     f32x2 ps2 = (f32x2){0.f, 0.f};
; #pragma unroll
;     for (int r = 0; r < 16; r += 2) { s0[r] = __builtin_amdgcn_exp2f(s0[r]); s0[r + 1] = __builtin_amdgcn_exp2f(s0[r + 1]); s1[r] = __builtin_amdgcn_exp2f(s1[r]); s1[r + 1] = __builtin_amdgcn_exp2f(s1[r + 1]);
;         ps2 += (f32x2){s0[r], s0[r + 1]}; ps2 += (f32x2){s1[r], s1[r + 1]}; }
;     l_run += ps2[0] + ps2[1];
;     u32x4 pw[4];
; #pragma unroll
;     for (int i = 0; i < 4; ++i) { pw[0][i] = cvtpk(s0[2 * i], s0[2 * i + 1]); pw[1][i] = cvtpk(s0[8 + 2 * i], s0[8 + 2 * i + 1]); pw[2][i] = cvtpk(s1[2 * i], s1[2 * i + 1]); pw[3][i] = cvtpk(s1[8 + 2 * i], s1[8 + 2 * i + 1]); }
; #pragma unroll
;     for (int kk = 0; kk < 4; ++kk) {
;         const bf16x8 pf = __builtin_bit_cast(bf16x8, pw[kk]);
;         { const s16x4 lo = vlo[2 * kk], hh = vhh[2 * kk];
;           const bf16x8 vf = (bf16x8){lo[0], lo[1], lo[2], lo[3], hh[0], hh[1], hh[2], hh[3]};
;           o0 = __builtin_amdgcn_mfma_f32_32x32x16_bf16(vf, pf, o0, 0, 0, 0); }
;         { const s16x4 lo = vlo[2 * kk + 1], hh = vhh[2 * kk + 1];
;           const bf16x8 vf = (bf16x8){lo[0], lo[1], lo[2], lo[3], hh[0], hh[1], hh[2], hh[3]};
;           o1 = __builtin_amdgcn_mfma_f32_32x32x16_bf16(vf, pf, o1, 0, 0, 0); }
;     }
.LBB0_459:
	s_or_b64 exec, exec, s[46:47]
	s_nop 6
	v_max_f32_e32 v14, v80, v81
	v_max3_f32 v15, v82, v83, v65
	v_max3_f32 v14, v14, v64, v66
	v_max3_f32 v14, v14, v67, v84
	v_max3_f32 v15, v15, v86, v87
	v_max3_f32 v14, v14, v85, v68
	v_max3_f32 v15, v15, v70, v71
	v_max3_f32 v14, v14, v69, v88
	v_max3_f32 v15, v15, v90, v91
	v_max3_f32 v14, v14, v89, v72
	v_max3_f32 v15, v15, v74, v75
	v_max3_f32 v14, v14, v73, v92
	v_max3_f32 v15, v15, v94, v95
	v_max3_f32 v14, v14, v93, v76
	v_max3_f32 v15, v15, v78, v79
	v_max3_f32 v14, v14, v77, v15
	v_mov_b32_e32 v15, v14
	s_nop 1
	v_permlane32_swap_b32_e32 v14, v15
	v_max_f32_e32 v14, v14, v15
	v_cmp_lt_f32_e32 vcc, s53, v14
	s_cbranch_vccz .LBB0_461
	v_max_f32_e32 v14, v14, v14
	v_max_f32_e32 v15, 0, v14
	v_exp_f32_e64 v14, -v15
	v_add_f32_e32 v1, v1, v15
	v_xor_b32_e32 v48, 0x80000000, v1
	v_sub_f32_e32 v80, v80, v15
	v_mul_f32_e32 v218, v218, v14
	v_pk_mul_f32 v[46:47], v[46:47], v[14:15] op_sel_hi:[1,0]
	v_pk_mul_f32 v[44:45], v[44:45], v[14:15] op_sel_hi:[1,0]
	v_pk_mul_f32 v[42:43], v[42:43], v[14:15] op_sel_hi:[1,0]
	v_pk_mul_f32 v[40:41], v[40:41], v[14:15] op_sel_hi:[1,0]
	v_pk_mul_f32 v[38:39], v[38:39], v[14:15] op_sel_hi:[1,0]
	v_pk_mul_f32 v[36:37], v[36:37], v[14:15] op_sel_hi:[1,0]
	v_pk_mul_f32 v[34:35], v[34:35], v[14:15] op_sel_hi:[1,0]
	v_pk_mul_f32 v[32:33], v[32:33], v[14:15] op_sel_hi:[1,0]
	v_pk_mul_f32 v[30:31], v[30:31], v[14:15] op_sel_hi:[1,0]
	v_pk_mul_f32 v[28:29], v[28:29], v[14:15] op_sel_hi:[1,0]
	v_pk_mul_f32 v[26:27], v[26:27], v[14:15] op_sel_hi:[1,0]
	v_pk_mul_f32 v[24:25], v[24:25], v[14:15] op_sel_hi:[1,0]
	v_pk_mul_f32 v[22:23], v[22:23], v[14:15] op_sel_hi:[1,0]
	v_pk_mul_f32 v[20:21], v[20:21], v[14:15] op_sel_hi:[1,0]
	v_pk_mul_f32 v[18:19], v[18:19], v[14:15] op_sel_hi:[1,0]
	v_pk_mul_f32 v[16:17], v[16:17], v[14:15] op_sel_hi:[1,0]
	v_sub_f32_e32 v81, v81, v15
	v_sub_f32_e32 v82, v82, v15
	v_sub_f32_e32 v83, v83, v15
	v_sub_f32_e32 v84, v84, v15
	v_sub_f32_e32 v85, v85, v15
	v_sub_f32_e32 v86, v86, v15
	v_sub_f32_e32 v87, v87, v15
	v_sub_f32_e32 v88, v88, v15
	v_sub_f32_e32 v89, v89, v15
	v_sub_f32_e32 v90, v90, v15
	v_sub_f32_e32 v91, v91, v15
	v_sub_f32_e32 v92, v92, v15
	v_sub_f32_e32 v93, v93, v15
	v_sub_f32_e32 v94, v94, v15
	v_sub_f32_e32 v95, v95, v15
	v_sub_f32_e32 v64, v64, v15
	v_sub_f32_e32 v65, v65, v15
	v_sub_f32_e32 v66, v66, v15
	v_sub_f32_e32 v67, v67, v15
	v_sub_f32_e32 v68, v68, v15
	v_sub_f32_e32 v69, v69, v15
	v_sub_f32_e32 v70, v70, v15
	v_sub_f32_e32 v71, v71, v15
	v_sub_f32_e32 v72, v72, v15
	v_sub_f32_e32 v73, v73, v15
	v_sub_f32_e32 v74, v74, v15
	v_sub_f32_e32 v75, v75, v15
	v_sub_f32_e32 v76, v76, v15
	v_sub_f32_e32 v77, v77, v15
	v_sub_f32_e32 v78, v78, v15
	v_sub_f32_e32 v79, v79, v15
	v_mov_b32_e32 v49, v48
	v_mov_b32_e32 v50, v48
	v_mov_b32_e32 v51, v48
	v_mov_b32_e32 v52, v48
	v_mov_b32_e32 v53, v48
	v_mov_b32_e32 v54, v48
	v_mov_b32_e32 v55, v48
	v_mov_b32_e32 v56, v48
	v_mov_b32_e32 v57, v48
	v_mov_b32_e32 v58, v48
	v_mov_b32_e32 v59, v48
	v_mov_b32_e32 v60, v48
	v_mov_b32_e32 v61, v48
	v_mov_b32_e32 v62, v48
	v_mov_b32_e32 v63, v48
.LBB0_461:
	v_exp_f32_e32 v14, v80
	v_exp_f32_e32 v15, v81
	v_exp_f32_e32 v160, v82
	v_exp_f32_e32 v161, v83
	v_exp_f32_e32 v84, v84
	v_exp_f32_e32 v85, v85
	v_exp_f32_e32 v86, v86
	v_exp_f32_e32 v87, v87
	v_cvt_pk_bf16_f32 v80, v14, v15
	v_cvt_pk_bf16_f32 v81, v160, v161
	v_cvt_pk_bf16_f32 v82, v84, v85
	v_cvt_pk_bf16_f32 v83, v86, v87
	v_exp_f32_e32 v156, v64
	v_exp_f32_e32 v157, v65
	s_waitcnt lgkmcnt(6)
	v_mfma_f32_32x32x16_bf16 v[32:47], v[152:155], v[80:83], v[32:47]
	v_exp_f32_e32 v88, v88
	v_exp_f32_e32 v89, v89
	v_exp_f32_e32 v90, v90
	v_exp_f32_e32 v91, v91
	v_exp_f32_e32 v92, v92
	v_exp_f32_e32 v93, v93
	v_add_f32_e32 v64, 0, v14
	v_add_f32_e32 v65, 0, v15
	s_waitcnt lgkmcnt(5)
	v_mfma_f32_32x32x16_bf16 v[16:31], v[148:151], v[80:83], v[16:31]
	v_exp_f32_e32 v80, v94
	v_exp_f32_e32 v81, v95
	v_add_f32_e32 v158, v156, v64
	v_add_f32_e32 v159, v157, v65
	v_exp_f32_e32 v162, v66
	v_exp_f32_e32 v163, v67
	v_cvt_pk_bf16_f32 v64, v88, v89
	v_cvt_pk_bf16_f32 v65, v90, v91
	v_cvt_pk_bf16_f32 v66, v92, v93
	v_cvt_pk_bf16_f32 v67, v80, v81
	v_exp_f32_e32 v14, v68
	v_exp_f32_e32 v15, v69
	v_mfma_f32_32x32x16_bf16 v[32:47], v[144:147], v[64:67], v[32:47]
	v_exp_f32_e32 v70, v70
	v_exp_f32_e32 v71, v71
	v_add_f32_e32 v68, v160, v158
	v_add_f32_e32 v69, v161, v159
	v_exp_f32_e32 v72, v72
	v_add_f32_e32 v68, v162, v68
	v_add_f32_e32 v69, v163, v69
	v_exp_f32_e32 v73, v73
	v_add_f32_e32 v68, v84, v68
	v_add_f32_e32 v69, v85, v69
	s_waitcnt lgkmcnt(4)
	v_mfma_f32_32x32x16_bf16 v[16:31], v[140:143], v[64:67], v[16:31]
	v_cvt_pk_bf16_f32 v64, v156, v157
	v_cvt_pk_bf16_f32 v65, v162, v163
	v_cvt_pk_bf16_f32 v66, v14, v15
	v_cvt_pk_bf16_f32 v67, v70, v71
	v_add_f32_e64 v68, v14, v68
	v_add_f32_e64 v69, v15, v69
	v_add_f32_e32 v68, v86, v68
	v_add_f32_e32 v69, v87, v69
	s_waitcnt lgkmcnt(3)
	v_mfma_f32_32x32x16_bf16 v[32:47], v[136:139], v[64:67], v[32:47]
	v_add_f32_e64 v14, v70, v68
	v_add_f32_e64 v15, v71, v69
	v_exp_f32_e32 v68, v74
	v_exp_f32_e32 v69, v75
	v_exp_f32_e32 v70, v76
	v_exp_f32_e32 v71, v77
	v_add_f32_e32 v14, v88, v14
	v_add_f32_e32 v15, v89, v15
	s_waitcnt lgkmcnt(2)
	v_mfma_f32_32x32x16_bf16 v[16:31], v[10:13], v[64:67], v[16:31]
	v_exp_f32_e32 v64, v78
	v_exp_f32_e32 v65, v79
	v_add_f32_e32 v14, v72, v14
	v_add_f32_e32 v15, v73, v15
	v_cvt_pk_bf16_f32 v10, v72, v73
	v_cvt_pk_bf16_f32 v11, v68, v69
	v_cvt_pk_bf16_f32 v12, v70, v71
	v_cvt_pk_bf16_f32 v13, v64, v65
	v_add_f32_e32 v14, v90, v14
	v_add_f32_e32 v15, v91, v15
	s_waitcnt lgkmcnt(1)
	v_mfma_f32_32x32x16_bf16 v[32:47], v[6:9], v[10:13], v[32:47]
	v_add_f32_e64 v6, v68, v14
	v_add_f32_e64 v7, v69, v15
	v_add_f32_e64 v6, v92, v6
	v_add_f32_e64 v7, v93, v7
	v_add_f32_e64 v6, v70, v6
	v_add_f32_e64 v7, v71, v7
	v_add_f32_e32 v6, v80, v6
	v_add_f32_e32 v7, v81, v7
	s_waitcnt lgkmcnt(0)
	v_mfma_f32_32x32x16_bf16 v[16:31], v[2:5], v[10:13], v[16:31]
	v_add_f32_e64 v6, v64, v6
	v_add_f32_e64 v7, v65, v7
	v_add_f32_e32 v6, v6, v7
	v_add_f32_e32 v218, v218, v6
